# gelu tail peephole in A1/A2 epilogues: max+fma(-|v|) replaces mul+fma+cmp+cndmask (125 sites)
# baseline (speedup 1.0000x reference)
.LBB0_329:
	s_andn2_b64 vcc, exec, s[0:1]
	s_cbranch_vccnz .LBB0_322
	v_min_u32_e32 v130, 32, v222
	v_lshlrev_b64 v[128:129], v130, v[202:203]
	v_min_u32_e32 v128, 1, v128
	v_or_b32_e32 v128, v129, v128
	v_min_u32_e32 v132, 32, v221
	v_cvt_f32_u32_e32 v131, v128
	v_lshlrev_b64 v[128:129], v132, v[200:201]
	v_min_u32_e32 v128, 1, v128
	v_or_b32_e32 v128, v129, v128
	v_cvt_f32_u32_e32 v128, v128
	v_sub_u32_e32 v129, 32, v130
	v_sub_u32_e32 v130, 32, v132
	v_ldexp_f32 v129, v131, v129
	v_ldexp_f32 v128, v128, v130
	s_mov_b32 s30, 0x35800000
	s_mov_b32 s0, 0x358637bd
	v_pk_mul_f32 v[130:131], v[128:129], s[30:31] op_sel_hi:[1,0]
	v_mov_b64_e32 v[128:129], s[0:1]
	v_pk_fma_f32 v[130:131], v[130:131], s[2:3], v[128:129] op_sel_hi:[1,0,0]
	v_lshl_add_u64 v[132:133], s[96:97], 0, v[204:205]
	v_mul_f32_e32 v134, 0x4b800000, v131
	v_cmp_gt_f32_e32 vcc, s89, v131
	s_lshl_b32 s98, s10, 9
	v_lshl_add_u64 v[132:133], v[132:133], 0, s[98:99]
	v_cndmask_b32_e32 v131, v131, v134, vcc
	v_rsq_f32_e32 v131, v131
	v_lshl_add_u64 v[132:133], v[132:133], 0, v[144:145]
	v_mul_f32_e32 v134, 0x45800000, v131
	v_cndmask_b32_e32 v134, v131, v134, vcc
	v_pk_mul_f32 v[124:125], v[124:125], v[134:135] op_sel_hi:[1,0]
	v_pk_mul_f32 v[136:137], v[122:123], v[134:135] op_sel_hi:[1,0]
	v_fma_f32 v131, |v124|, s26, 1.0
	v_rcp_f32_e32 v131, v131
	v_pk_mul_f32 v[122:123], v[120:121], v[134:135] op_sel_hi:[1,0]
	v_mul_f32_e32 v121, v124, v124
	v_mul_f32_e32 v121, 0xbf38aa3b, v121
	v_fmamk_f32 v120, v131, 0x3f07dc22, v211
	v_fmaak_f32 v120, v131, v120, 0x3f35f0e3
	v_fmaak_f32 v120, v131, v120, 0xbe11a98e
	v_exp_f32_e32 v121, v121
	v_fmaak_f32 v120, v131, v120, 0x3e027906
	v_mul_f32_e32 v120, v131, v120
	v_fma_f32 v131, |v125|, s26, 1.0
	v_rcp_f32_e32 v131, v131
	v_mul_f32_e32 v120, v121, v120
	v_max_f32_e32 v121, 0, v124
	v_fma_f32 v120, -|v124|, v120, v121
	v_mul_f32_e32 v124, v125, v125
	v_mul_f32_e32 v124, 0xbf38aa3b, v124
	v_fmamk_f32 v121, v131, 0x3f07dc22, v211
	v_fmaak_f32 v121, v131, v121, 0x3f35f0e3
	v_exp_f32_e32 v124, v124
	v_fmaak_f32 v121, v131, v121, 0xbe11a98e
	v_pk_mul_f32 v[126:127], v[126:127], v[134:135] op_sel_hi:[1,0]
	v_fmaak_f32 v121, v131, v121, 0x3e027906
	v_mul_f32_e32 v121, v131, v121
	v_fma_f32 v131, |v126|, s26, 1.0
	v_rcp_f32_e32 v131, v131
	v_mul_f32_e32 v121, v124, v121
	v_max_f32_e32 v124, 0, v125
	v_fma_f32 v121, -|v125|, v121, v124
	v_fma_f32 v125, |v127|, s26, 1.0
	v_rcp_f32_e32 v125, v125
	v_mul_f32_e32 v124, v126, v126
	v_cvt_pk_bf16_f32 v120, v120, v121
	v_fmamk_f32 v121, v131, 0x3f07dc22, v211
	v_mul_f32_e32 v124, 0xbf38aa3b, v124
	v_fmaak_f32 v121, v131, v121, 0x3f35f0e3
	v_exp_f32_e32 v124, v124
	v_fmaak_f32 v121, v131, v121, 0xbe11a98e
	v_fmaak_f32 v121, v131, v121, 0x3e027906
	v_mul_f32_e32 v121, v131, v121
	v_mul_f32_e32 v121, v124, v121
	v_max_f32_e32 v124, 0, v126
	v_fma_f32 v121, -|v126|, v121, v124
	v_mul_f32_e32 v126, v127, v127
	v_mul_f32_e32 v126, 0xbf38aa3b, v126
	v_fmamk_f32 v124, v125, 0x3f07dc22, v211
	v_fmaak_f32 v124, v125, v124, 0x3f35f0e3
	v_exp_f32_e32 v126, v126
	v_fmaak_f32 v124, v125, v124, 0xbe11a98e
	v_fmaak_f32 v124, v125, v124, 0x3e027906
	v_mul_f32_e32 v124, v125, v124
	v_mul_f32_e32 v124, v126, v124
	v_fma_f32 v126, |v122|, s26, 1.0
	v_rcp_f32_e32 v126, v126
	v_max_f32_e32 v125, 0, v127
	v_fma_f32 v124, -|v127|, v124, v125
	v_pk_mul_f32 v[116:117], v[116:117], v[134:135] op_sel_hi:[1,0]
	v_pk_mul_f32 v[118:119], v[118:119], v[134:135] op_sel_hi:[1,0]
	v_cvt_pk_bf16_f32 v121, v121, v124
	v_fmamk_f32 v124, v126, 0x3f07dc22, v211
	v_fmaak_f32 v124, v126, v124, 0x3f35f0e3
	v_mul_f32_e32 v125, v122, v122
	v_mul_f32_e32 v125, 0xbf38aa3b, v125
	v_fmaak_f32 v124, v126, v124, 0xbe11a98e
	v_exp_f32_e32 v125, v125
	v_fmaak_f32 v124, v126, v124, 0x3e027906
	v_mul_f32_e32 v124, v126, v124
	v_fma_f32 v126, |v123|, s26, 1.0
	v_rcp_f32_e32 v126, v126
	v_mul_f32_e32 v124, v125, v124
	v_max_f32_e32 v125, 0, v122
	v_fma_f32 v122, -|v122|, v124, v125
	v_fmamk_f32 v124, v126, 0x3f07dc22, v211
	v_mul_f32_e32 v125, v123, v123
	v_fmaak_f32 v124, v126, v124, 0x3f35f0e3
	v_mul_f32_e32 v125, 0xbf38aa3b, v125
	v_exp_f32_e32 v125, v125
	v_fmaak_f32 v124, v126, v124, 0xbe11a98e
	v_fmaak_f32 v124, v126, v124, 0x3e027906
	v_mul_f32_e32 v124, v126, v124
	v_fma_f32 v126, |v136|, s26, 1.0
	v_rcp_f32_e32 v126, v126
	v_mul_f32_e32 v124, v125, v124
	v_max_f32_e32 v125, 0, v123
	v_fma_f32 v123, -|v123|, v124, v125
	v_mul_f32_e32 v124, v136, v136
	v_cvt_pk_bf16_f32 v122, v122, v123
	v_fmamk_f32 v123, v126, 0x3f07dc22, v211
	v_mul_f32_e32 v124, 0xbf38aa3b, v124
	v_fmaak_f32 v123, v126, v123, 0x3f35f0e3
	v_exp_f32_e32 v124, v124
	v_fmaak_f32 v123, v126, v123, 0xbe11a98e
	v_fma_f32 v125, |v137|, s26, 1.0
	v_fmaak_f32 v123, v126, v123, 0x3e027906
	v_rcp_f32_e32 v125, v125
	v_mul_f32_e32 v123, v126, v123
	v_mul_f32_e32 v123, v124, v123
	v_max_f32_e32 v124, 0, v136
	v_fma_f32 v123, -|v136|, v123, v124
	v_mul_f32_e32 v126, v137, v137
	v_mul_f32_e32 v126, 0xbf38aa3b, v126
	v_fmamk_f32 v124, v125, 0x3f07dc22, v211
	v_fmaak_f32 v124, v125, v124, 0x3f35f0e3
	v_exp_f32_e32 v126, v126
	v_fmaak_f32 v124, v125, v124, 0xbe11a98e
	v_fmaak_f32 v124, v125, v124, 0x3e027906
	v_mul_f32_e32 v124, v125, v124
	v_mul_f32_e32 v124, v126, v124
	v_max_f32_e32 v125, 0, v137
	v_fma_f32 v124, -|v137|, v124, v125
	v_cvt_pk_bf16_f32 v123, v123, v124
	global_store_dwordx4 v[132:133], v[120:123], off
	s_nop 0
	v_fma_f32 v120, |v116|, s26, 1.0
	v_rcp_f32_e32 v122, v120
	v_pk_mul_f32 v[120:121], v[114:115], v[134:135] op_sel_hi:[1,0]
	v_pk_mul_f32 v[114:115], v[112:113], v[134:135] op_sel_hi:[1,0]
	v_mul_f32_e32 v113, v116, v116
	v_fmamk_f32 v112, v122, 0x3f07dc22, v211
	v_fmaak_f32 v112, v122, v112, 0x3f35f0e3
	v_mul_f32_e32 v113, 0xbf38aa3b, v113
	v_fmaak_f32 v112, v122, v112, 0xbe11a98e
	v_exp_f32_e32 v113, v113
	v_fmaak_f32 v112, v122, v112, 0x3e027906
	v_mul_f32_e32 v112, v122, v112
	v_fma_f32 v122, |v117|, s26, 1.0
	v_rcp_f32_e32 v122, v122
	v_mul_f32_e32 v112, v113, v112
	v_max_f32_e32 v113, 0, v116
	v_fma_f32 v112, -|v116|, v112, v113
	v_fmamk_f32 v113, v122, 0x3f07dc22, v211
	v_mul_f32_e32 v116, v117, v117
	v_fmaak_f32 v113, v122, v113, 0x3f35f0e3
	v_mul_f32_e32 v116, 0xbf38aa3b, v116
	v_exp_f32_e32 v116, v116
	v_fmaak_f32 v113, v122, v113, 0xbe11a98e
	v_fmaak_f32 v113, v122, v113, 0x3e027906
	v_mul_f32_e32 v113, v122, v113
	v_fma_f32 v122, |v118|, s26, 1.0
	v_rcp_f32_e32 v122, v122
	v_mul_f32_e32 v113, v116, v113
	v_max_f32_e32 v116, 0, v117
	v_fma_f32 v113, -|v117|, v113, v116
	v_fma_f32 v117, |v119|, s26, 1.0
	v_rcp_f32_e32 v117, v117
	v_mul_f32_e32 v116, v118, v118
	v_cvt_pk_bf16_f32 v112, v112, v113
	v_fmamk_f32 v113, v122, 0x3f07dc22, v211
	v_mul_f32_e32 v116, 0xbf38aa3b, v116
	v_fmaak_f32 v113, v122, v113, 0x3f35f0e3
	v_exp_f32_e32 v116, v116
	v_fmaak_f32 v113, v122, v113, 0xbe11a98e
	v_fmaak_f32 v113, v122, v113, 0x3e027906
	v_mul_f32_e32 v113, v122, v113
	v_mul_f32_e32 v113, v116, v113
	v_max_f32_e32 v116, 0, v118
	v_fma_f32 v113, -|v118|, v113, v116
	v_mul_f32_e32 v118, v119, v119
	v_mul_f32_e32 v118, 0xbf38aa3b, v118
	v_fmamk_f32 v116, v117, 0x3f07dc22, v211
	v_fmaak_f32 v116, v117, v116, 0x3f35f0e3
	v_exp_f32_e32 v118, v118
	v_fmaak_f32 v116, v117, v116, 0xbe11a98e
	v_fmaak_f32 v116, v117, v116, 0x3e027906
	v_mul_f32_e32 v116, v117, v116
	v_mul_f32_e32 v116, v118, v116
	v_fma_f32 v118, |v114|, s26, 1.0
	v_rcp_f32_e32 v118, v118
	v_max_f32_e32 v117, 0, v119
	v_fma_f32 v116, -|v119|, v116, v117
	s_nop 0
	v_cvt_pk_bf16_f32 v113, v113, v116
	v_fmamk_f32 v116, v118, 0x3f07dc22, v211
	v_fmaak_f32 v116, v118, v116, 0x3f35f0e3
	v_mul_f32_e32 v117, v114, v114
	v_mul_f32_e32 v117, 0xbf38aa3b, v117
	v_fmaak_f32 v116, v118, v116, 0xbe11a98e
	v_exp_f32_e32 v117, v117
	v_fmaak_f32 v116, v118, v116, 0x3e027906
	v_mul_f32_e32 v116, v118, v116
	v_fma_f32 v118, |v115|, s26, 1.0
	v_rcp_f32_e32 v118, v118
	v_mul_f32_e32 v116, v117, v116
	v_max_f32_e32 v117, 0, v114
	v_fma_f32 v114, -|v114|, v116, v117
	v_fmamk_f32 v116, v118, 0x3f07dc22, v211
	v_mul_f32_e32 v117, v115, v115
	v_fmaak_f32 v116, v118, v116, 0x3f35f0e3
	v_mul_f32_e32 v117, 0xbf38aa3b, v117
	v_exp_f32_e32 v117, v117
	v_fmaak_f32 v116, v118, v116, 0xbe11a98e
	v_fmaak_f32 v116, v118, v116, 0x3e027906
	v_mul_f32_e32 v116, v118, v116
	v_fma_f32 v118, |v120|, s26, 1.0
	v_rcp_f32_e32 v118, v118
	v_mul_f32_e32 v116, v117, v116
	v_max_f32_e32 v117, 0, v115
	v_fma_f32 v115, -|v115|, v116, v117
	v_mul_f32_e32 v116, v120, v120
	v_cvt_pk_bf16_f32 v114, v114, v115
	v_fmamk_f32 v115, v118, 0x3f07dc22, v211
	v_mul_f32_e32 v116, 0xbf38aa3b, v116
	v_fmaak_f32 v115, v118, v115, 0x3f35f0e3
	v_exp_f32_e32 v116, v116
	v_fmaak_f32 v115, v118, v115, 0xbe11a98e
	v_fma_f32 v117, |v121|, s26, 1.0
	v_fmaak_f32 v115, v118, v115, 0x3e027906
	v_rcp_f32_e32 v117, v117
	v_mul_f32_e32 v115, v118, v115
	v_mul_f32_e32 v115, v116, v115
	v_max_f32_e32 v116, 0, v120
	v_fma_f32 v115, -|v120|, v115, v116
	v_mul_f32_e32 v118, v121, v121
	v_mul_f32_e32 v118, 0xbf38aa3b, v118
	v_fmamk_f32 v116, v117, 0x3f07dc22, v211
	v_fmaak_f32 v116, v117, v116, 0x3f35f0e3
	v_exp_f32_e32 v118, v118
	v_fmaak_f32 v116, v117, v116, 0xbe11a98e
	v_fmaak_f32 v116, v117, v116, 0x3e027906
	v_mul_f32_e32 v116, v117, v116
	v_mul_f32_e32 v116, v118, v116
	v_mul_f32_e32 v118, 0x4b800000, v130
	v_cmp_gt_f32_e32 vcc, s89, v130
	v_max_f32_e32 v117, 0, v121
	v_fma_f32 v116, -|v121|, v116, v117
	v_cndmask_b32_e32 v118, v130, v118, vcc
	v_rsq_f32_e32 v118, v118
	v_cvt_pk_bf16_f32 v115, v115, v116
	global_store_dwordx4 v[132:133], v[112:115], off offset:64
	s_nop 1
	v_mul_f32_e32 v112, 0x45800000, v118
	v_cndmask_b32_e32 v112, v118, v112, vcc
	v_pk_mul_f32 v[108:109], v[108:109], v[112:113] op_sel_hi:[1,0]
	s_nop 0
	v_fma_f32 v113, |v108|, s26, 1.0
	v_rcp_f32_e32 v113, v113
	v_pk_mul_f32 v[114:115], v[106:107], v[112:113] op_sel_hi:[1,0]
	v_pk_mul_f32 v[106:107], v[104:105], v[112:113] op_sel_hi:[1,0]
	v_fmamk_f32 v104, v113, 0x3f07dc22, v211
	v_fmaak_f32 v104, v113, v104, 0x3f35f0e3
	v_mul_f32_e32 v105, v108, v108
	v_mul_f32_e32 v105, 0xbf38aa3b, v105
	v_fmaak_f32 v104, v113, v104, 0xbe11a98e
	v_exp_f32_e32 v105, v105
	v_fmaak_f32 v104, v113, v104, 0x3e027906
	v_pk_mul_f32 v[110:111], v[110:111], v[112:113] op_sel_hi:[1,0]
	v_mul_f32_e32 v104, v113, v104
	v_fma_f32 v113, |v109|, s26, 1.0
	v_rcp_f32_e32 v113, v113
	v_mul_f32_e32 v104, v105, v104
	v_max_f32_e32 v105, 0, v108
	v_fma_f32 v104, -|v108|, v104, v105
	v_fmamk_f32 v105, v113, 0x3f07dc22, v211
	v_mul_f32_e32 v108, v109, v109
	v_fmaak_f32 v105, v113, v105, 0x3f35f0e3
	v_mul_f32_e32 v108, 0xbf38aa3b, v108
	v_exp_f32_e32 v108, v108
	v_fmaak_f32 v105, v113, v105, 0xbe11a98e
	v_fmaak_f32 v105, v113, v105, 0x3e027906
	v_mul_f32_e32 v105, v113, v105
	v_fma_f32 v113, |v110|, s26, 1.0
	v_rcp_f32_e32 v113, v113
	v_mul_f32_e32 v105, v108, v105
	v_max_f32_e32 v108, 0, v109
	v_fma_f32 v105, -|v109|, v105, v108
	v_fma_f32 v109, |v111|, s26, 1.0
	v_rcp_f32_e32 v109, v109
	v_mul_f32_e32 v108, v110, v110
	v_cvt_pk_bf16_f32 v104, v104, v105
	v_fmamk_f32 v105, v113, 0x3f07dc22, v211
	v_mul_f32_e32 v108, 0xbf38aa3b, v108
	v_fmaak_f32 v105, v113, v105, 0x3f35f0e3
	v_exp_f32_e32 v108, v108
	v_fmaak_f32 v105, v113, v105, 0xbe11a98e
	v_fmaak_f32 v105, v113, v105, 0x3e027906
	v_mul_f32_e32 v105, v113, v105
	v_mul_f32_e32 v105, v108, v105
	v_max_f32_e32 v108, 0, v110
	v_fma_f32 v105, -|v110|, v105, v108
	v_mul_f32_e32 v110, v111, v111
	v_mul_f32_e32 v110, 0xbf38aa3b, v110
	v_fmamk_f32 v108, v109, 0x3f07dc22, v211
	v_fmaak_f32 v108, v109, v108, 0x3f35f0e3
	v_exp_f32_e32 v110, v110
	v_fmaak_f32 v108, v109, v108, 0xbe11a98e
	v_fmaak_f32 v108, v109, v108, 0x3e027906
	v_mul_f32_e32 v108, v109, v108
	v_mul_f32_e32 v108, v110, v108
	v_fma_f32 v110, |v106|, s26, 1.0
	v_rcp_f32_e32 v110, v110
	v_max_f32_e32 v109, 0, v111
	v_fma_f32 v108, -|v111|, v108, v109
	v_pk_mul_f32 v[100:101], v[100:101], v[112:113] op_sel_hi:[1,0]
	v_pk_mul_f32 v[102:103], v[102:103], v[112:113] op_sel_hi:[1,0]
	v_cvt_pk_bf16_f32 v105, v105, v108
	v_fmamk_f32 v108, v110, 0x3f07dc22, v211
	v_fmaak_f32 v108, v110, v108, 0x3f35f0e3
	v_mul_f32_e32 v109, v106, v106
	v_mul_f32_e32 v109, 0xbf38aa3b, v109
	v_fmaak_f32 v108, v110, v108, 0xbe11a98e
	v_exp_f32_e32 v109, v109
	v_fmaak_f32 v108, v110, v108, 0x3e027906
	v_mul_f32_e32 v108, v110, v108
	v_fma_f32 v110, |v107|, s26, 1.0
	v_rcp_f32_e32 v110, v110
	v_mul_f32_e32 v108, v109, v108
	v_max_f32_e32 v109, 0, v106
	v_fma_f32 v106, -|v106|, v108, v109
	v_fmamk_f32 v108, v110, 0x3f07dc22, v211
	v_mul_f32_e32 v109, v107, v107
	v_fmaak_f32 v108, v110, v108, 0x3f35f0e3
	v_mul_f32_e32 v109, 0xbf38aa3b, v109
	v_exp_f32_e32 v109, v109
	v_fmaak_f32 v108, v110, v108, 0xbe11a98e
	v_fmaak_f32 v108, v110, v108, 0x3e027906
	v_mul_f32_e32 v108, v110, v108
	v_fma_f32 v110, |v114|, s26, 1.0
	v_rcp_f32_e32 v110, v110
	v_mul_f32_e32 v108, v109, v108
	v_max_f32_e32 v109, 0, v107
	v_fma_f32 v107, -|v107|, v108, v109
	v_mul_f32_e32 v108, v114, v114
	v_cvt_pk_bf16_f32 v106, v106, v107
	v_fmamk_f32 v107, v110, 0x3f07dc22, v211
	v_mul_f32_e32 v108, 0xbf38aa3b, v108
	v_fmaak_f32 v107, v110, v107, 0x3f35f0e3
	v_exp_f32_e32 v108, v108
	v_fmaak_f32 v107, v110, v107, 0xbe11a98e
	v_fma_f32 v109, |v115|, s26, 1.0
	v_fmaak_f32 v107, v110, v107, 0x3e027906
	v_rcp_f32_e32 v109, v109
	v_mul_f32_e32 v107, v110, v107
	v_mul_f32_e32 v107, v108, v107
	v_max_f32_e32 v108, 0, v114
	v_fma_f32 v107, -|v114|, v107, v108
	v_mul_f32_e32 v110, v115, v115
	v_mul_f32_e32 v110, 0xbf38aa3b, v110
	v_fmamk_f32 v108, v109, 0x3f07dc22, v211
	v_fmaak_f32 v108, v109, v108, 0x3f35f0e3
	v_exp_f32_e32 v110, v110
	v_fmaak_f32 v108, v109, v108, 0xbe11a98e
	v_fmaak_f32 v108, v109, v108, 0x3e027906
	v_mul_f32_e32 v108, v109, v108
	v_mul_f32_e32 v108, v110, v108
	v_max_f32_e32 v109, 0, v115
	v_fma_f32 v108, -|v115|, v108, v109
	v_cvt_pk_bf16_f32 v107, v107, v108
	v_lshl_add_u64 v[108:109], s[96:97], 0, v[198:199]
	v_lshl_add_u64 v[108:109], v[108:109], 0, s[98:99]
	v_lshl_add_u64 v[108:109], v[108:109], 0, v[144:145]
	global_store_dwordx4 v[108:109], v[104:107], off
	s_nop 0
	v_fma_f32 v104, |v100|, s26, 1.0
	v_rcp_f32_e32 v106, v104
	v_pk_mul_f32 v[104:105], v[98:99], v[112:113] op_sel_hi:[1,0]
	v_pk_mul_f32 v[98:99], v[96:97], v[112:113] op_sel_hi:[1,0]
	v_mul_f32_e32 v97, v100, v100
	v_fmamk_f32 v96, v106, 0x3f07dc22, v211
	v_fmaak_f32 v96, v106, v96, 0x3f35f0e3
	v_mul_f32_e32 v97, 0xbf38aa3b, v97
	v_fmaak_f32 v96, v106, v96, 0xbe11a98e
	v_exp_f32_e32 v97, v97
	v_fmaak_f32 v96, v106, v96, 0x3e027906
	v_mul_f32_e32 v96, v106, v96
	v_fma_f32 v106, |v101|, s26, 1.0
	v_rcp_f32_e32 v106, v106
	v_mul_f32_e32 v96, v97, v96
	v_max_f32_e32 v97, 0, v100
	v_fma_f32 v96, -|v100|, v96, v97
	v_fmamk_f32 v97, v106, 0x3f07dc22, v211
	v_mul_f32_e32 v100, v101, v101
	v_fmaak_f32 v97, v106, v97, 0x3f35f0e3
	v_mul_f32_e32 v100, 0xbf38aa3b, v100
	v_exp_f32_e32 v100, v100
	v_fmaak_f32 v97, v106, v97, 0xbe11a98e
	v_fmaak_f32 v97, v106, v97, 0x3e027906
	v_mul_f32_e32 v97, v106, v97
	v_fma_f32 v106, |v102|, s26, 1.0
	v_rcp_f32_e32 v106, v106
	v_mul_f32_e32 v97, v100, v97
	v_max_f32_e32 v100, 0, v101
	v_fma_f32 v97, -|v101|, v97, v100
	v_fma_f32 v101, |v103|, s26, 1.0
	v_rcp_f32_e32 v101, v101
	v_mul_f32_e32 v100, v102, v102
	v_cvt_pk_bf16_f32 v96, v96, v97
	v_fmamk_f32 v97, v106, 0x3f07dc22, v211
	v_mul_f32_e32 v100, 0xbf38aa3b, v100
	v_fmaak_f32 v97, v106, v97, 0x3f35f0e3
	v_exp_f32_e32 v100, v100
	v_fmaak_f32 v97, v106, v97, 0xbe11a98e
	v_fmaak_f32 v97, v106, v97, 0x3e027906
	v_mul_f32_e32 v97, v106, v97
	v_mul_f32_e32 v97, v100, v97
	v_max_f32_e32 v100, 0, v102
	v_fma_f32 v97, -|v102|, v97, v100
	v_mul_f32_e32 v102, v103, v103
	v_mul_f32_e32 v102, 0xbf38aa3b, v102
	v_fmamk_f32 v100, v101, 0x3f07dc22, v211
	v_fmaak_f32 v100, v101, v100, 0x3f35f0e3
	v_exp_f32_e32 v102, v102
	v_fmaak_f32 v100, v101, v100, 0xbe11a98e
	v_fmaak_f32 v100, v101, v100, 0x3e027906
	v_mul_f32_e32 v100, v101, v100
	v_mul_f32_e32 v100, v102, v100
	v_fma_f32 v102, |v98|, s26, 1.0
	v_rcp_f32_e32 v102, v102
	v_max_f32_e32 v101, 0, v103
	v_fma_f32 v100, -|v103|, v100, v101
	v_cvt_pk_bf16_f32 v97, v97, v100
	v_fmamk_f32 v100, v102, 0x3f07dc22, v211
	v_fmaak_f32 v100, v102, v100, 0x3f35f0e3
	v_mul_f32_e32 v101, v98, v98
	v_mul_f32_e32 v101, 0xbf38aa3b, v101
	v_fmaak_f32 v100, v102, v100, 0xbe11a98e
	v_exp_f32_e32 v101, v101
	v_fmaak_f32 v100, v102, v100, 0x3e027906
	v_mul_f32_e32 v100, v102, v100
	v_fma_f32 v102, |v99|, s26, 1.0
	v_rcp_f32_e32 v102, v102
	v_mul_f32_e32 v100, v101, v100
	v_max_f32_e32 v101, 0, v98
	v_fma_f32 v98, -|v98|, v100, v101
	v_fmamk_f32 v100, v102, 0x3f07dc22, v211
	v_mul_f32_e32 v101, v99, v99
	v_fmaak_f32 v100, v102, v100, 0x3f35f0e3
	v_mul_f32_e32 v101, 0xbf38aa3b, v101
	v_exp_f32_e32 v101, v101
	v_fmaak_f32 v100, v102, v100, 0xbe11a98e
	v_fmaak_f32 v100, v102, v100, 0x3e027906
	v_mul_f32_e32 v100, v102, v100
	v_fma_f32 v102, |v104|, s26, 1.0
	v_rcp_f32_e32 v102, v102
	v_mul_f32_e32 v100, v101, v100
	v_max_f32_e32 v101, 0, v99
	v_fma_f32 v99, -|v99|, v100, v101
	v_mul_f32_e32 v100, v104, v104
	v_cvt_pk_bf16_f32 v98, v98, v99
	v_fmamk_f32 v99, v102, 0x3f07dc22, v211
	v_mul_f32_e32 v100, 0xbf38aa3b, v100
	v_fmaak_f32 v99, v102, v99, 0x3f35f0e3
	v_exp_f32_e32 v100, v100
	v_fmaak_f32 v99, v102, v99, 0xbe11a98e
	v_fma_f32 v101, |v105|, s26, 1.0
	v_fmaak_f32 v99, v102, v99, 0x3e027906
	v_rcp_f32_e32 v101, v101
	v_mul_f32_e32 v99, v102, v99
	v_mul_f32_e32 v99, v100, v99
	v_max_f32_e32 v100, 0, v104
	v_fma_f32 v99, -|v104|, v99, v100
	v_mul_f32_e32 v102, v105, v105
	v_mul_f32_e32 v102, 0xbf38aa3b, v102
	v_fmamk_f32 v100, v101, 0x3f07dc22, v211
	v_fmaak_f32 v100, v101, v100, 0x3f35f0e3
	v_exp_f32_e32 v102, v102
	v_fmaak_f32 v100, v101, v100, 0xbe11a98e
	v_fmaak_f32 v100, v101, v100, 0x3e027906
	v_mul_f32_e32 v100, v101, v100
	v_mul_f32_e32 v100, v102, v100
	v_mul_f32_e32 v101, v105, v100
	v_fma_f32 v100, -v105, v100, v105
	v_cmp_gt_f32_e32 vcc, 0, v105
	s_nop 1
	v_cndmask_b32_e32 v100, v100, v101, vcc
	v_cvt_pk_bf16_f32 v99, v99, v100
	global_store_dwordx4 v[108:109], v[96:99], off offset:64
	v_min_u32_e32 v100, 32, v219
	s_nop 0
	v_min_u32_e32 v98, 32, v220
	v_lshlrev_b64 v[96:97], v98, v[192:193]
	v_min_u32_e32 v96, 1, v96
	v_or_b32_e32 v96, v97, v96
	v_cvt_f32_u32_e32 v99, v96
	v_lshlrev_b64 v[96:97], v100, v[196:197]
	v_min_u32_e32 v96, 1, v96
	v_or_b32_e32 v96, v97, v96
	v_cvt_f32_u32_e32 v96, v96
	v_sub_u32_e32 v97, 32, v98
	v_sub_u32_e32 v98, 32, v100
	v_ldexp_f32 v97, v99, v97
	v_ldexp_f32 v96, v96, v98
	v_pk_mul_f32 v[96:97], v[96:97], s[30:31] op_sel_hi:[1,0]
	s_nop 0
	v_pk_fma_f32 v[96:97], v[96:97], s[2:3], v[128:129] op_sel_hi:[1,0,0]
	s_nop 0
	v_mul_f32_e32 v98, 0x4b800000, v97
	v_cmp_gt_f32_e32 vcc, s89, v97
	s_nop 1
	v_cndmask_b32_e32 v97, v97, v98, vcc
	v_rsq_f32_e32 v97, v97
	v_lshl_add_u64 v[98:99], s[96:97], 0, v[194:195]
	v_lshl_add_u64 v[98:99], v[98:99], 0, s[98:99]
	v_lshl_add_u64 v[98:99], v[98:99], 0, v[144:145]
	v_mul_f32_e32 v100, 0x45800000, v97
	v_cndmask_b32_e32 v100, v97, v100, vcc
	v_pk_mul_f32 v[92:93], v[92:93], v[100:101] op_sel_hi:[1,0]
	v_pk_mul_f32 v[102:103], v[90:91], v[100:101] op_sel_hi:[1,0]
	v_fma_f32 v97, |v92|, s26, 1.0
	v_rcp_f32_e32 v97, v97
	v_pk_mul_f32 v[90:91], v[88:89], v[100:101] op_sel_hi:[1,0]
	v_mul_f32_e32 v89, v92, v92
	v_mul_f32_e32 v89, 0xbf38aa3b, v89
	v_fmamk_f32 v88, v97, 0x3f07dc22, v211
	v_fmaak_f32 v88, v97, v88, 0x3f35f0e3
	v_fmaak_f32 v88, v97, v88, 0xbe11a98e
	v_exp_f32_e32 v89, v89
	v_fmaak_f32 v88, v97, v88, 0x3e027906
	v_mul_f32_e32 v88, v97, v88
	v_fma_f32 v97, |v93|, s26, 1.0
	v_rcp_f32_e32 v97, v97
	v_mul_f32_e32 v88, v89, v88
	v_max_f32_e32 v89, 0, v92
	v_fma_f32 v88, -|v92|, v88, v89
	v_mul_f32_e32 v92, v93, v93
	v_mul_f32_e32 v92, 0xbf38aa3b, v92
	v_fmamk_f32 v89, v97, 0x3f07dc22, v211
	v_fmaak_f32 v89, v97, v89, 0x3f35f0e3
	v_exp_f32_e32 v92, v92
	v_fmaak_f32 v89, v97, v89, 0xbe11a98e
	v_pk_mul_f32 v[94:95], v[94:95], v[100:101] op_sel_hi:[1,0]
	v_fmaak_f32 v89, v97, v89, 0x3e027906
	v_mul_f32_e32 v89, v97, v89
	v_fma_f32 v97, |v94|, s26, 1.0
	v_rcp_f32_e32 v97, v97
	v_mul_f32_e32 v89, v92, v89
	v_max_f32_e32 v92, 0, v93
	v_fma_f32 v89, -|v93|, v89, v92
	v_fma_f32 v93, |v95|, s26, 1.0
	v_rcp_f32_e32 v93, v93
	v_mul_f32_e32 v92, v94, v94
	v_cvt_pk_bf16_f32 v88, v88, v89
	v_fmamk_f32 v89, v97, 0x3f07dc22, v211
	v_mul_f32_e32 v92, 0xbf38aa3b, v92
	v_fmaak_f32 v89, v97, v89, 0x3f35f0e3
	v_exp_f32_e32 v92, v92
	v_fmaak_f32 v89, v97, v89, 0xbe11a98e
	v_fmaak_f32 v89, v97, v89, 0x3e027906
	v_mul_f32_e32 v89, v97, v89
	v_mul_f32_e32 v89, v92, v89
	v_max_f32_e32 v92, 0, v94
	v_fma_f32 v89, -|v94|, v89, v92
	v_mul_f32_e32 v94, v95, v95
	v_mul_f32_e32 v94, 0xbf38aa3b, v94
	v_fmamk_f32 v92, v93, 0x3f07dc22, v211
	v_fmaak_f32 v92, v93, v92, 0x3f35f0e3
	v_exp_f32_e32 v94, v94
	v_fmaak_f32 v92, v93, v92, 0xbe11a98e
	v_fmaak_f32 v92, v93, v92, 0x3e027906
	v_mul_f32_e32 v92, v93, v92
	v_mul_f32_e32 v92, v94, v92
	v_fma_f32 v94, |v90|, s26, 1.0
	v_rcp_f32_e32 v94, v94
	v_max_f32_e32 v93, 0, v95
	v_fma_f32 v92, -|v95|, v92, v93
	v_pk_mul_f32 v[84:85], v[84:85], v[100:101] op_sel_hi:[1,0]
	v_pk_mul_f32 v[86:87], v[86:87], v[100:101] op_sel_hi:[1,0]
	v_cvt_pk_bf16_f32 v89, v89, v92
	v_fmamk_f32 v92, v94, 0x3f07dc22, v211
	v_fmaak_f32 v92, v94, v92, 0x3f35f0e3
	v_mul_f32_e32 v93, v90, v90
	v_mul_f32_e32 v93, 0xbf38aa3b, v93
	v_fmaak_f32 v92, v94, v92, 0xbe11a98e
	v_exp_f32_e32 v93, v93
	v_fmaak_f32 v92, v94, v92, 0x3e027906
	v_mul_f32_e32 v92, v94, v92
	v_fma_f32 v94, |v91|, s26, 1.0
	v_rcp_f32_e32 v94, v94
	v_mul_f32_e32 v92, v93, v92
	v_max_f32_e32 v93, 0, v90
	v_fma_f32 v90, -|v90|, v92, v93
	v_fmamk_f32 v92, v94, 0x3f07dc22, v211
	v_mul_f32_e32 v93, v91, v91
	v_fmaak_f32 v92, v94, v92, 0x3f35f0e3
	v_mul_f32_e32 v93, 0xbf38aa3b, v93
	v_exp_f32_e32 v93, v93
	v_fmaak_f32 v92, v94, v92, 0xbe11a98e
	v_fmaak_f32 v92, v94, v92, 0x3e027906
	v_mul_f32_e32 v92, v94, v92
	v_fma_f32 v94, |v102|, s26, 1.0
	v_rcp_f32_e32 v94, v94
	v_mul_f32_e32 v92, v93, v92
	v_max_f32_e32 v93, 0, v91
	v_fma_f32 v91, -|v91|, v92, v93
	v_mul_f32_e32 v92, v102, v102
	v_cvt_pk_bf16_f32 v90, v90, v91
	v_fmamk_f32 v91, v94, 0x3f07dc22, v211
	v_mul_f32_e32 v92, 0xbf38aa3b, v92
	v_fmaak_f32 v91, v94, v91, 0x3f35f0e3
	v_exp_f32_e32 v92, v92
	v_fmaak_f32 v91, v94, v91, 0xbe11a98e
	v_fma_f32 v93, |v103|, s26, 1.0
	v_fmaak_f32 v91, v94, v91, 0x3e027906
	v_rcp_f32_e32 v93, v93
	v_mul_f32_e32 v91, v94, v91
	v_mul_f32_e32 v91, v92, v91
	v_max_f32_e32 v92, 0, v102
	v_fma_f32 v91, -|v102|, v91, v92
	v_mul_f32_e32 v94, v103, v103
	v_mul_f32_e32 v94, 0xbf38aa3b, v94
	v_fmamk_f32 v92, v93, 0x3f07dc22, v211
	v_fmaak_f32 v92, v93, v92, 0x3f35f0e3
	v_exp_f32_e32 v94, v94
	v_fmaak_f32 v92, v93, v92, 0xbe11a98e
	v_fmaak_f32 v92, v93, v92, 0x3e027906
	v_mul_f32_e32 v92, v93, v92
	v_mul_f32_e32 v92, v94, v92
	v_max_f32_e32 v93, 0, v103
	v_fma_f32 v92, -|v103|, v92, v93
	v_cvt_pk_bf16_f32 v91, v91, v92
	global_store_dwordx4 v[98:99], v[88:91], off
	s_nop 0
	v_fma_f32 v88, |v84|, s26, 1.0
	v_rcp_f32_e32 v90, v88
	v_pk_mul_f32 v[88:89], v[82:83], v[100:101] op_sel_hi:[1,0]
	v_pk_mul_f32 v[82:83], v[80:81], v[100:101] op_sel_hi:[1,0]
	v_mul_f32_e32 v81, v84, v84
	v_fmamk_f32 v80, v90, 0x3f07dc22, v211
	v_fmaak_f32 v80, v90, v80, 0x3f35f0e3
	v_mul_f32_e32 v81, 0xbf38aa3b, v81
	v_fmaak_f32 v80, v90, v80, 0xbe11a98e
	v_exp_f32_e32 v81, v81
	v_fmaak_f32 v80, v90, v80, 0x3e027906
	v_mul_f32_e32 v80, v90, v80
	v_fma_f32 v90, |v85|, s26, 1.0
	v_rcp_f32_e32 v90, v90
	v_mul_f32_e32 v80, v81, v80
	v_max_f32_e32 v81, 0, v84
	v_fma_f32 v80, -|v84|, v80, v81
	v_fmamk_f32 v81, v90, 0x3f07dc22, v211
	v_mul_f32_e32 v84, v85, v85
	v_fmaak_f32 v81, v90, v81, 0x3f35f0e3
	v_mul_f32_e32 v84, 0xbf38aa3b, v84
	v_exp_f32_e32 v84, v84
	v_fmaak_f32 v81, v90, v81, 0xbe11a98e
	v_fmaak_f32 v81, v90, v81, 0x3e027906
	v_mul_f32_e32 v81, v90, v81
	v_fma_f32 v90, |v86|, s26, 1.0
	v_rcp_f32_e32 v90, v90
	v_mul_f32_e32 v81, v84, v81
	v_max_f32_e32 v84, 0, v85
	v_fma_f32 v81, -|v85|, v81, v84
	v_fma_f32 v85, |v87|, s26, 1.0
	v_rcp_f32_e32 v85, v85
	v_mul_f32_e32 v84, v86, v86
	v_cvt_pk_bf16_f32 v80, v80, v81
	v_fmamk_f32 v81, v90, 0x3f07dc22, v211
	v_mul_f32_e32 v84, 0xbf38aa3b, v84
	v_fmaak_f32 v81, v90, v81, 0x3f35f0e3
	v_exp_f32_e32 v84, v84
	v_fmaak_f32 v81, v90, v81, 0xbe11a98e
	v_fmaak_f32 v81, v90, v81, 0x3e027906
	v_mul_f32_e32 v81, v90, v81
	v_mul_f32_e32 v81, v84, v81
	v_max_f32_e32 v84, 0, v86
	v_fma_f32 v81, -|v86|, v81, v84
	v_mul_f32_e32 v86, v87, v87
	v_mul_f32_e32 v86, 0xbf38aa3b, v86
	v_fmamk_f32 v84, v85, 0x3f07dc22, v211
	v_fmaak_f32 v84, v85, v84, 0x3f35f0e3
	v_exp_f32_e32 v86, v86
	v_fmaak_f32 v84, v85, v84, 0xbe11a98e
	v_fmaak_f32 v84, v85, v84, 0x3e027906
	v_mul_f32_e32 v84, v85, v84
	v_mul_f32_e32 v84, v86, v84
	v_fma_f32 v86, |v82|, s26, 1.0
	v_rcp_f32_e32 v86, v86
	v_max_f32_e32 v85, 0, v87
	v_fma_f32 v84, -|v87|, v84, v85
	s_nop 0
	v_cvt_pk_bf16_f32 v81, v81, v84
	v_fmamk_f32 v84, v86, 0x3f07dc22, v211
	v_fmaak_f32 v84, v86, v84, 0x3f35f0e3
	v_mul_f32_e32 v85, v82, v82
	v_mul_f32_e32 v85, 0xbf38aa3b, v85
	v_fmaak_f32 v84, v86, v84, 0xbe11a98e
	v_exp_f32_e32 v85, v85
	v_fmaak_f32 v84, v86, v84, 0x3e027906
	v_mul_f32_e32 v84, v86, v84
	v_fma_f32 v86, |v83|, s26, 1.0
	v_rcp_f32_e32 v86, v86
	v_mul_f32_e32 v84, v85, v84
	v_max_f32_e32 v85, 0, v82
	v_fma_f32 v82, -|v82|, v84, v85
	v_fmamk_f32 v84, v86, 0x3f07dc22, v211
	v_mul_f32_e32 v85, v83, v83
	v_fmaak_f32 v84, v86, v84, 0x3f35f0e3
	v_mul_f32_e32 v85, 0xbf38aa3b, v85
	v_exp_f32_e32 v85, v85
	v_fmaak_f32 v84, v86, v84, 0xbe11a98e
	v_fmaak_f32 v84, v86, v84, 0x3e027906
	v_mul_f32_e32 v84, v86, v84
	v_fma_f32 v86, |v88|, s26, 1.0
	v_rcp_f32_e32 v86, v86
	v_mul_f32_e32 v84, v85, v84
	v_max_f32_e32 v85, 0, v83
	v_fma_f32 v83, -|v83|, v84, v85
	v_mul_f32_e32 v84, v88, v88
	v_cvt_pk_bf16_f32 v82, v82, v83
	v_fmamk_f32 v83, v86, 0x3f07dc22, v211
	v_mul_f32_e32 v84, 0xbf38aa3b, v84
	v_fmaak_f32 v83, v86, v83, 0x3f35f0e3
	v_exp_f32_e32 v84, v84
	v_fmaak_f32 v83, v86, v83, 0xbe11a98e
	v_fma_f32 v85, |v89|, s26, 1.0
	v_fmaak_f32 v83, v86, v83, 0x3e027906
	v_rcp_f32_e32 v85, v85
	v_mul_f32_e32 v83, v86, v83
	v_mul_f32_e32 v83, v84, v83
	v_max_f32_e32 v84, 0, v88
	v_fma_f32 v83, -|v88|, v83, v84
	v_mul_f32_e32 v86, v89, v89
	v_mul_f32_e32 v86, 0xbf38aa3b, v86
	v_fmamk_f32 v84, v85, 0x3f07dc22, v211
	v_fmaak_f32 v84, v85, v84, 0x3f35f0e3
	v_exp_f32_e32 v86, v86
	v_fmaak_f32 v84, v85, v84, 0xbe11a98e
	v_fmaak_f32 v84, v85, v84, 0x3e027906
	v_mul_f32_e32 v84, v85, v84
	v_mul_f32_e32 v84, v86, v84
	v_mul_f32_e32 v86, 0x4b800000, v96
	v_cmp_gt_f32_e32 vcc, s89, v96
	v_max_f32_e32 v85, 0, v89
	v_fma_f32 v84, -|v89|, v84, v85
	v_cndmask_b32_e32 v86, v96, v86, vcc
	v_rsq_f32_e32 v86, v86
	v_cvt_pk_bf16_f32 v83, v83, v84
	global_store_dwordx4 v[98:99], v[80:83], off offset:64
	s_nop 1
	v_mul_f32_e32 v80, 0x45800000, v86
	v_cndmask_b32_e32 v80, v86, v80, vcc
	v_pk_mul_f32 v[76:77], v[76:77], v[80:81] op_sel_hi:[1,0]
	s_nop 0
	v_fma_f32 v81, |v76|, s26, 1.0
	v_rcp_f32_e32 v81, v81
	v_pk_mul_f32 v[82:83], v[74:75], v[80:81] op_sel_hi:[1,0]
	v_pk_mul_f32 v[74:75], v[72:73], v[80:81] op_sel_hi:[1,0]
	v_fmamk_f32 v72, v81, 0x3f07dc22, v211
	v_fmaak_f32 v72, v81, v72, 0x3f35f0e3
	v_mul_f32_e32 v73, v76, v76
	v_mul_f32_e32 v73, 0xbf38aa3b, v73
	v_fmaak_f32 v72, v81, v72, 0xbe11a98e
	v_exp_f32_e32 v73, v73
	v_fmaak_f32 v72, v81, v72, 0x3e027906
	v_pk_mul_f32 v[78:79], v[78:79], v[80:81] op_sel_hi:[1,0]
	v_mul_f32_e32 v72, v81, v72
	v_fma_f32 v81, |v77|, s26, 1.0
	v_rcp_f32_e32 v81, v81
	v_mul_f32_e32 v72, v73, v72
	v_max_f32_e32 v73, 0, v76
	v_fma_f32 v72, -|v76|, v72, v73
	v_fmamk_f32 v73, v81, 0x3f07dc22, v211
	v_mul_f32_e32 v76, v77, v77
	v_fmaak_f32 v73, v81, v73, 0x3f35f0e3
	v_mul_f32_e32 v76, 0xbf38aa3b, v76
	v_exp_f32_e32 v76, v76
	v_fmaak_f32 v73, v81, v73, 0xbe11a98e
	v_fmaak_f32 v73, v81, v73, 0x3e027906
	v_mul_f32_e32 v73, v81, v73
	v_fma_f32 v81, |v78|, s26, 1.0
	v_rcp_f32_e32 v81, v81
	v_mul_f32_e32 v73, v76, v73
	v_max_f32_e32 v76, 0, v77
	v_fma_f32 v73, -|v77|, v73, v76
	v_fma_f32 v77, |v79|, s26, 1.0
	v_rcp_f32_e32 v77, v77
	v_mul_f32_e32 v76, v78, v78
	v_cvt_pk_bf16_f32 v72, v72, v73
	v_fmamk_f32 v73, v81, 0x3f07dc22, v211
	v_mul_f32_e32 v76, 0xbf38aa3b, v76
	v_fmaak_f32 v73, v81, v73, 0x3f35f0e3
	v_exp_f32_e32 v76, v76
	v_fmaak_f32 v73, v81, v73, 0xbe11a98e
	v_fmaak_f32 v73, v81, v73, 0x3e027906
	v_mul_f32_e32 v73, v81, v73
	v_mul_f32_e32 v73, v76, v73
	v_max_f32_e32 v76, 0, v78
	v_fma_f32 v73, -|v78|, v73, v76
	v_mul_f32_e32 v78, v79, v79
	v_mul_f32_e32 v78, 0xbf38aa3b, v78
	v_fmamk_f32 v76, v77, 0x3f07dc22, v211
	v_fmaak_f32 v76, v77, v76, 0x3f35f0e3
	v_exp_f32_e32 v78, v78
	v_fmaak_f32 v76, v77, v76, 0xbe11a98e
	v_fmaak_f32 v76, v77, v76, 0x3e027906
	v_mul_f32_e32 v76, v77, v76
	v_mul_f32_e32 v76, v78, v76
	v_fma_f32 v78, |v74|, s26, 1.0
	v_rcp_f32_e32 v78, v78
	v_max_f32_e32 v77, 0, v79
	v_fma_f32 v76, -|v79|, v76, v77
	v_pk_mul_f32 v[68:69], v[68:69], v[80:81] op_sel_hi:[1,0]
	v_pk_mul_f32 v[70:71], v[70:71], v[80:81] op_sel_hi:[1,0]
	v_cvt_pk_bf16_f32 v73, v73, v76
	v_fmamk_f32 v76, v78, 0x3f07dc22, v211
	v_fmaak_f32 v76, v78, v76, 0x3f35f0e3
	v_mul_f32_e32 v77, v74, v74
	v_mul_f32_e32 v77, 0xbf38aa3b, v77
	v_fmaak_f32 v76, v78, v76, 0xbe11a98e
	v_exp_f32_e32 v77, v77
	v_fmaak_f32 v76, v78, v76, 0x3e027906
	v_mul_f32_e32 v76, v78, v76
	v_fma_f32 v78, |v75|, s26, 1.0
	v_rcp_f32_e32 v78, v78
	v_mul_f32_e32 v76, v77, v76
	v_max_f32_e32 v77, 0, v74
	v_fma_f32 v74, -|v74|, v76, v77
	v_fmamk_f32 v76, v78, 0x3f07dc22, v211
	v_mul_f32_e32 v77, v75, v75
	v_fmaak_f32 v76, v78, v76, 0x3f35f0e3
	v_mul_f32_e32 v77, 0xbf38aa3b, v77
	v_exp_f32_e32 v77, v77
	v_fmaak_f32 v76, v78, v76, 0xbe11a98e
	v_fmaak_f32 v76, v78, v76, 0x3e027906
	v_mul_f32_e32 v76, v78, v76
	v_fma_f32 v78, |v82|, s26, 1.0
	v_rcp_f32_e32 v78, v78
	v_mul_f32_e32 v76, v77, v76
	v_max_f32_e32 v77, 0, v75
	v_fma_f32 v75, -|v75|, v76, v77
	v_mul_f32_e32 v76, v82, v82
	v_cvt_pk_bf16_f32 v74, v74, v75
	v_fmamk_f32 v75, v78, 0x3f07dc22, v211
	v_mul_f32_e32 v76, 0xbf38aa3b, v76
	v_fmaak_f32 v75, v78, v75, 0x3f35f0e3
	v_exp_f32_e32 v76, v76
	v_fmaak_f32 v75, v78, v75, 0xbe11a98e
	v_fma_f32 v77, |v83|, s26, 1.0
	v_fmaak_f32 v75, v78, v75, 0x3e027906
	v_rcp_f32_e32 v77, v77
	v_mul_f32_e32 v75, v78, v75
	v_mul_f32_e32 v75, v76, v75
	v_max_f32_e32 v76, 0, v82
	v_fma_f32 v75, -|v82|, v75, v76
	v_mul_f32_e32 v78, v83, v83
	v_mul_f32_e32 v78, 0xbf38aa3b, v78
	v_fmamk_f32 v76, v77, 0x3f07dc22, v211
	v_fmaak_f32 v76, v77, v76, 0x3f35f0e3
	v_exp_f32_e32 v78, v78
	v_fmaak_f32 v76, v77, v76, 0xbe11a98e
	v_fmaak_f32 v76, v77, v76, 0x3e027906
	v_mul_f32_e32 v76, v77, v76
	v_mul_f32_e32 v76, v78, v76
	v_max_f32_e32 v77, 0, v83
	v_fma_f32 v76, -|v83|, v76, v77
	v_cvt_pk_bf16_f32 v75, v75, v76
	v_lshl_add_u64 v[76:77], s[96:97], 0, v[190:191]
	v_lshl_add_u64 v[76:77], v[76:77], 0, s[98:99]
	v_lshl_add_u64 v[76:77], v[76:77], 0, v[144:145]
	global_store_dwordx4 v[76:77], v[72:75], off
	s_nop 0
	v_fma_f32 v72, |v68|, s26, 1.0
	v_rcp_f32_e32 v74, v72
	v_pk_mul_f32 v[72:73], v[66:67], v[80:81] op_sel_hi:[1,0]
	v_pk_mul_f32 v[66:67], v[64:65], v[80:81] op_sel_hi:[1,0]
	v_mul_f32_e32 v65, v68, v68
	v_fmamk_f32 v64, v74, 0x3f07dc22, v211
	v_fmaak_f32 v64, v74, v64, 0x3f35f0e3
	v_mul_f32_e32 v65, 0xbf38aa3b, v65
	v_fmaak_f32 v64, v74, v64, 0xbe11a98e
	v_exp_f32_e32 v65, v65
	v_fmaak_f32 v64, v74, v64, 0x3e027906
	v_mul_f32_e32 v64, v74, v64
	v_fma_f32 v74, |v69|, s26, 1.0
	v_rcp_f32_e32 v74, v74
	v_mul_f32_e32 v64, v65, v64
	v_max_f32_e32 v65, 0, v68
	v_fma_f32 v64, -|v68|, v64, v65
	v_fmamk_f32 v65, v74, 0x3f07dc22, v211
	v_mul_f32_e32 v68, v69, v69
	v_fmaak_f32 v65, v74, v65, 0x3f35f0e3
	v_mul_f32_e32 v68, 0xbf38aa3b, v68
	v_exp_f32_e32 v68, v68
	v_fmaak_f32 v65, v74, v65, 0xbe11a98e
	v_fmaak_f32 v65, v74, v65, 0x3e027906
	v_mul_f32_e32 v65, v74, v65
	v_fma_f32 v74, |v70|, s26, 1.0
	v_rcp_f32_e32 v74, v74
	v_mul_f32_e32 v65, v68, v65
	v_max_f32_e32 v68, 0, v69
	v_fma_f32 v65, -|v69|, v65, v68
	v_fma_f32 v69, |v71|, s26, 1.0
	v_rcp_f32_e32 v69, v69
	v_mul_f32_e32 v68, v70, v70
	v_cvt_pk_bf16_f32 v64, v64, v65
	v_fmamk_f32 v65, v74, 0x3f07dc22, v211
	v_mul_f32_e32 v68, 0xbf38aa3b, v68
	v_fmaak_f32 v65, v74, v65, 0x3f35f0e3
	v_exp_f32_e32 v68, v68
	v_fmaak_f32 v65, v74, v65, 0xbe11a98e
	v_fmaak_f32 v65, v74, v65, 0x3e027906
	v_mul_f32_e32 v65, v74, v65
	v_mul_f32_e32 v65, v68, v65
	v_max_f32_e32 v68, 0, v70
	v_fma_f32 v65, -|v70|, v65, v68
	v_mul_f32_e32 v70, v71, v71
	v_mul_f32_e32 v70, 0xbf38aa3b, v70
	v_fmamk_f32 v68, v69, 0x3f07dc22, v211
	v_fmaak_f32 v68, v69, v68, 0x3f35f0e3
	v_exp_f32_e32 v70, v70
	v_fmaak_f32 v68, v69, v68, 0xbe11a98e
	v_fmaak_f32 v68, v69, v68, 0x3e027906
	v_mul_f32_e32 v68, v69, v68
	v_mul_f32_e32 v68, v70, v68
	v_fma_f32 v70, |v66|, s26, 1.0
	v_rcp_f32_e32 v70, v70
	v_max_f32_e32 v69, 0, v71
	v_fma_f32 v68, -|v71|, v68, v69
	v_cvt_pk_bf16_f32 v65, v65, v68
	v_fmamk_f32 v68, v70, 0x3f07dc22, v211
	v_fmaak_f32 v68, v70, v68, 0x3f35f0e3
	v_mul_f32_e32 v69, v66, v66
	v_mul_f32_e32 v69, 0xbf38aa3b, v69
	v_fmaak_f32 v68, v70, v68, 0xbe11a98e
	v_exp_f32_e32 v69, v69
	v_fmaak_f32 v68, v70, v68, 0x3e027906
	v_mul_f32_e32 v68, v70, v68
	v_fma_f32 v70, |v67|, s26, 1.0
	v_rcp_f32_e32 v70, v70
	v_mul_f32_e32 v68, v69, v68
	v_max_f32_e32 v69, 0, v66
	v_fma_f32 v66, -|v66|, v68, v69
	v_fmamk_f32 v68, v70, 0x3f07dc22, v211
	v_mul_f32_e32 v69, v67, v67
	v_fmaak_f32 v68, v70, v68, 0x3f35f0e3
	v_mul_f32_e32 v69, 0xbf38aa3b, v69
	v_exp_f32_e32 v69, v69
	v_fmaak_f32 v68, v70, v68, 0xbe11a98e
	v_fmaak_f32 v68, v70, v68, 0x3e027906
	v_mul_f32_e32 v68, v70, v68
	v_fma_f32 v70, |v72|, s26, 1.0
	v_rcp_f32_e32 v70, v70
	v_mul_f32_e32 v68, v69, v68
	v_max_f32_e32 v69, 0, v67
	v_fma_f32 v67, -|v67|, v68, v69
	v_mul_f32_e32 v68, v72, v72
	v_cvt_pk_bf16_f32 v66, v66, v67
	v_fmamk_f32 v67, v70, 0x3f07dc22, v211
	v_mul_f32_e32 v68, 0xbf38aa3b, v68
	v_fmaak_f32 v67, v70, v67, 0x3f35f0e3
	v_exp_f32_e32 v68, v68
	v_fmaak_f32 v67, v70, v67, 0xbe11a98e
	v_fma_f32 v69, |v73|, s26, 1.0
	v_fmaak_f32 v67, v70, v67, 0x3e027906
	v_rcp_f32_e32 v69, v69
	v_mul_f32_e32 v67, v70, v67
	v_mul_f32_e32 v67, v68, v67
	v_max_f32_e32 v68, 0, v72
	v_fma_f32 v67, -|v72|, v67, v68
	v_mul_f32_e32 v70, v73, v73
	v_mul_f32_e32 v70, 0xbf38aa3b, v70
	v_fmamk_f32 v68, v69, 0x3f07dc22, v211
	v_fmaak_f32 v68, v69, v68, 0x3f35f0e3
	v_exp_f32_e32 v70, v70
	v_fmaak_f32 v68, v69, v68, 0xbe11a98e
	v_fmaak_f32 v68, v69, v68, 0x3e027906
	v_mul_f32_e32 v68, v69, v68
	v_mul_f32_e32 v68, v70, v68
	v_mul_f32_e32 v69, v73, v68
	v_fma_f32 v68, -v73, v68, v73
	v_cmp_gt_f32_e32 vcc, 0, v73
	s_nop 1
	v_cndmask_b32_e32 v68, v68, v69, vcc
	v_cvt_pk_bf16_f32 v67, v67, v68
	global_store_dwordx4 v[76:77], v[64:67], off offset:64
	s_nop 1
	v_ffbh_u32_e32 v64, v167
	v_min_u32_e32 v66, 32, v64
	v_lshlrev_b64 v[64:65], v66, v[166:167]
	v_min_u32_e32 v64, 1, v64
	v_or_b32_e32 v64, v65, v64
	v_cvt_f32_u32_e32 v67, v64
	v_ffbh_u32_e32 v64, v189
	v_min_u32_e32 v68, 32, v64
	v_lshlrev_b64 v[64:65], v68, v[188:189]
	v_min_u32_e32 v64, 1, v64
	v_or_b32_e32 v64, v65, v64
	v_cvt_f32_u32_e32 v64, v64
	v_sub_u32_e32 v65, 32, v66
	v_sub_u32_e32 v66, 32, v68
	v_ldexp_f32 v65, v67, v65
	v_ldexp_f32 v64, v64, v66
	v_pk_mul_f32 v[64:65], v[64:65], s[30:31] op_sel_hi:[1,0]
	v_lshlrev_b64 v[66:67], 10, v[168:169]
	v_pk_fma_f32 v[64:65], v[64:65], s[2:3], v[128:129] op_sel_hi:[1,0,0]
	v_lshl_add_u64 v[66:67], s[96:97], 0, v[66:67]
	v_mul_f32_e32 v68, 0x4b800000, v65
	v_cmp_gt_f32_e32 vcc, s89, v65
	v_lshl_add_u64 v[66:67], v[66:67], 0, s[98:99]
	v_lshl_add_u64 v[66:67], v[66:67], 0, v[144:145]
	v_cndmask_b32_e32 v65, v65, v68, vcc
	v_rsq_f32_e32 v65, v65
	s_nop 0
	v_mul_f32_e32 v68, 0x45800000, v65
	v_cndmask_b32_e32 v68, v65, v68, vcc
	v_pk_mul_f32 v[60:61], v[60:61], v[68:69] op_sel_hi:[1,0]
	v_pk_mul_f32 v[70:71], v[58:59], v[68:69] op_sel_hi:[1,0]
	v_fma_f32 v65, |v60|, s26, 1.0
	v_rcp_f32_e32 v65, v65
	v_pk_mul_f32 v[58:59], v[56:57], v[68:69] op_sel_hi:[1,0]
	v_mul_f32_e32 v57, v60, v60
	v_mul_f32_e32 v57, 0xbf38aa3b, v57
	v_fmamk_f32 v56, v65, 0x3f07dc22, v211
	v_fmaak_f32 v56, v65, v56, 0x3f35f0e3
	v_fmaak_f32 v56, v65, v56, 0xbe11a98e
	v_exp_f32_e32 v57, v57
	v_fmaak_f32 v56, v65, v56, 0x3e027906
	v_mul_f32_e32 v56, v65, v56
	v_fma_f32 v65, |v61|, s26, 1.0
	v_rcp_f32_e32 v65, v65
	v_mul_f32_e32 v56, v57, v56
	v_max_f32_e32 v57, 0, v60
	v_fma_f32 v56, -|v60|, v56, v57
	v_mul_f32_e32 v60, v61, v61
	v_mul_f32_e32 v60, 0xbf38aa3b, v60
	v_fmamk_f32 v57, v65, 0x3f07dc22, v211
	v_fmaak_f32 v57, v65, v57, 0x3f35f0e3
	v_exp_f32_e32 v60, v60
	v_fmaak_f32 v57, v65, v57, 0xbe11a98e
	v_pk_mul_f32 v[62:63], v[62:63], v[68:69] op_sel_hi:[1,0]
	v_fmaak_f32 v57, v65, v57, 0x3e027906
	v_mul_f32_e32 v57, v65, v57
	v_fma_f32 v65, |v62|, s26, 1.0
	v_rcp_f32_e32 v65, v65
	v_mul_f32_e32 v57, v60, v57
	v_max_f32_e32 v60, 0, v61
	v_fma_f32 v57, -|v61|, v57, v60
	v_fma_f32 v61, |v63|, s26, 1.0
	v_rcp_f32_e32 v61, v61
	v_mul_f32_e32 v60, v62, v62
	v_cvt_pk_bf16_f32 v56, v56, v57
	v_fmamk_f32 v57, v65, 0x3f07dc22, v211
	v_mul_f32_e32 v60, 0xbf38aa3b, v60
	v_fmaak_f32 v57, v65, v57, 0x3f35f0e3
	v_exp_f32_e32 v60, v60
	v_fmaak_f32 v57, v65, v57, 0xbe11a98e
	v_fmaak_f32 v57, v65, v57, 0x3e027906
	v_mul_f32_e32 v57, v65, v57
	v_mul_f32_e32 v57, v60, v57
	v_max_f32_e32 v60, 0, v62
	v_fma_f32 v57, -|v62|, v57, v60
	v_mul_f32_e32 v62, v63, v63
	v_mul_f32_e32 v62, 0xbf38aa3b, v62
	v_fmamk_f32 v60, v61, 0x3f07dc22, v211
	v_fmaak_f32 v60, v61, v60, 0x3f35f0e3
	v_exp_f32_e32 v62, v62
	v_fmaak_f32 v60, v61, v60, 0xbe11a98e
	v_fmaak_f32 v60, v61, v60, 0x3e027906
	v_mul_f32_e32 v60, v61, v60
	v_mul_f32_e32 v60, v62, v60
	v_fma_f32 v62, |v58|, s26, 1.0
	v_rcp_f32_e32 v62, v62
	v_max_f32_e32 v61, 0, v63
	v_fma_f32 v60, -|v63|, v60, v61
	v_pk_mul_f32 v[52:53], v[52:53], v[68:69] op_sel_hi:[1,0]
	v_pk_mul_f32 v[54:55], v[54:55], v[68:69] op_sel_hi:[1,0]
	v_cvt_pk_bf16_f32 v57, v57, v60
	v_fmamk_f32 v60, v62, 0x3f07dc22, v211
	v_fmaak_f32 v60, v62, v60, 0x3f35f0e3
	v_mul_f32_e32 v61, v58, v58
	v_mul_f32_e32 v61, 0xbf38aa3b, v61
	v_fmaak_f32 v60, v62, v60, 0xbe11a98e
	v_exp_f32_e32 v61, v61
	v_fmaak_f32 v60, v62, v60, 0x3e027906
	v_mul_f32_e32 v60, v62, v60
	v_fma_f32 v62, |v59|, s26, 1.0
	v_rcp_f32_e32 v62, v62
	v_mul_f32_e32 v60, v61, v60
	v_max_f32_e32 v61, 0, v58
	v_fma_f32 v58, -|v58|, v60, v61
	v_fmamk_f32 v60, v62, 0x3f07dc22, v211
	v_mul_f32_e32 v61, v59, v59
	v_fmaak_f32 v60, v62, v60, 0x3f35f0e3
	v_mul_f32_e32 v61, 0xbf38aa3b, v61
	v_exp_f32_e32 v61, v61
	v_fmaak_f32 v60, v62, v60, 0xbe11a98e
	v_fmaak_f32 v60, v62, v60, 0x3e027906
	v_mul_f32_e32 v60, v62, v60
	v_fma_f32 v62, |v70|, s26, 1.0
	v_rcp_f32_e32 v62, v62
	v_mul_f32_e32 v60, v61, v60
	v_max_f32_e32 v61, 0, v59
	v_fma_f32 v59, -|v59|, v60, v61
	v_mul_f32_e32 v60, v70, v70
	v_cvt_pk_bf16_f32 v58, v58, v59
	v_fmamk_f32 v59, v62, 0x3f07dc22, v211
	v_mul_f32_e32 v60, 0xbf38aa3b, v60
	v_fmaak_f32 v59, v62, v59, 0x3f35f0e3
	v_exp_f32_e32 v60, v60
	v_fmaak_f32 v59, v62, v59, 0xbe11a98e
	v_fma_f32 v61, |v71|, s26, 1.0
	v_fmaak_f32 v59, v62, v59, 0x3e027906
	v_rcp_f32_e32 v61, v61
	v_mul_f32_e32 v59, v62, v59
	v_mul_f32_e32 v59, v60, v59
	v_max_f32_e32 v60, 0, v70
	v_fma_f32 v59, -|v70|, v59, v60
	v_mul_f32_e32 v62, v71, v71
	v_mul_f32_e32 v62, 0xbf38aa3b, v62
	v_fmamk_f32 v60, v61, 0x3f07dc22, v211
	v_fmaak_f32 v60, v61, v60, 0x3f35f0e3
	v_exp_f32_e32 v62, v62
	v_fmaak_f32 v60, v61, v60, 0xbe11a98e
	v_fmaak_f32 v60, v61, v60, 0x3e027906
	v_mul_f32_e32 v60, v61, v60
	v_mul_f32_e32 v60, v62, v60
	v_max_f32_e32 v61, 0, v71
	v_fma_f32 v60, -|v71|, v60, v61
	v_cvt_pk_bf16_f32 v59, v59, v60
	global_store_dwordx4 v[66:67], v[56:59], off
	s_nop 0
	v_fma_f32 v56, |v52|, s26, 1.0
	v_rcp_f32_e32 v58, v56
	v_pk_mul_f32 v[56:57], v[50:51], v[68:69] op_sel_hi:[1,0]
	v_pk_mul_f32 v[50:51], v[48:49], v[68:69] op_sel_hi:[1,0]
	v_mul_f32_e32 v49, v52, v52
	v_fmamk_f32 v48, v58, 0x3f07dc22, v211
	v_fmaak_f32 v48, v58, v48, 0x3f35f0e3
	v_mul_f32_e32 v49, 0xbf38aa3b, v49
	v_fmaak_f32 v48, v58, v48, 0xbe11a98e
	v_exp_f32_e32 v49, v49
	v_fmaak_f32 v48, v58, v48, 0x3e027906
	v_mul_f32_e32 v48, v58, v48
	v_fma_f32 v58, |v53|, s26, 1.0
	v_rcp_f32_e32 v58, v58
	v_mul_f32_e32 v48, v49, v48
	v_max_f32_e32 v49, 0, v52
	v_fma_f32 v48, -|v52|, v48, v49
	v_fmamk_f32 v49, v58, 0x3f07dc22, v211
	v_mul_f32_e32 v52, v53, v53
	v_fmaak_f32 v49, v58, v49, 0x3f35f0e3
	v_mul_f32_e32 v52, 0xbf38aa3b, v52
	v_exp_f32_e32 v52, v52
	v_fmaak_f32 v49, v58, v49, 0xbe11a98e
	v_fmaak_f32 v49, v58, v49, 0x3e027906
	v_mul_f32_e32 v49, v58, v49
	v_fma_f32 v58, |v54|, s26, 1.0
	v_rcp_f32_e32 v58, v58
	v_mul_f32_e32 v49, v52, v49
	v_max_f32_e32 v52, 0, v53
	v_fma_f32 v49, -|v53|, v49, v52
	v_fma_f32 v53, |v55|, s26, 1.0
	v_rcp_f32_e32 v53, v53
	v_mul_f32_e32 v52, v54, v54
	v_cvt_pk_bf16_f32 v48, v48, v49
	v_fmamk_f32 v49, v58, 0x3f07dc22, v211
	v_mul_f32_e32 v52, 0xbf38aa3b, v52
	v_fmaak_f32 v49, v58, v49, 0x3f35f0e3
	v_exp_f32_e32 v52, v52
	v_fmaak_f32 v49, v58, v49, 0xbe11a98e
	v_fmaak_f32 v49, v58, v49, 0x3e027906
	v_mul_f32_e32 v49, v58, v49
	v_mul_f32_e32 v49, v52, v49
	v_max_f32_e32 v52, 0, v54
	v_fma_f32 v49, -|v54|, v49, v52
	v_mul_f32_e32 v54, v55, v55
	v_mul_f32_e32 v54, 0xbf38aa3b, v54
	v_fmamk_f32 v52, v53, 0x3f07dc22, v211
	v_fmaak_f32 v52, v53, v52, 0x3f35f0e3
	v_exp_f32_e32 v54, v54
	v_fmaak_f32 v52, v53, v52, 0xbe11a98e
	v_fmaak_f32 v52, v53, v52, 0x3e027906
	v_mul_f32_e32 v52, v53, v52
	v_mul_f32_e32 v52, v54, v52
	v_fma_f32 v54, |v50|, s26, 1.0
	v_rcp_f32_e32 v54, v54
	v_max_f32_e32 v53, 0, v55
	v_fma_f32 v52, -|v55|, v52, v53
	s_nop 0
	v_cvt_pk_bf16_f32 v49, v49, v52
	v_fmamk_f32 v52, v54, 0x3f07dc22, v211
	v_fmaak_f32 v52, v54, v52, 0x3f35f0e3
	v_mul_f32_e32 v53, v50, v50
	v_mul_f32_e32 v53, 0xbf38aa3b, v53
	v_fmaak_f32 v52, v54, v52, 0xbe11a98e
	v_exp_f32_e32 v53, v53
	v_fmaak_f32 v52, v54, v52, 0x3e027906
	v_mul_f32_e32 v52, v54, v52
	v_fma_f32 v54, |v51|, s26, 1.0
	v_rcp_f32_e32 v54, v54
	v_mul_f32_e32 v52, v53, v52
	v_max_f32_e32 v53, 0, v50
	v_fma_f32 v50, -|v50|, v52, v53
	v_fmamk_f32 v52, v54, 0x3f07dc22, v211
	v_mul_f32_e32 v53, v51, v51
	v_fmaak_f32 v52, v54, v52, 0x3f35f0e3
	v_mul_f32_e32 v53, 0xbf38aa3b, v53
	v_exp_f32_e32 v53, v53
	v_fmaak_f32 v52, v54, v52, 0xbe11a98e
	v_fmaak_f32 v52, v54, v52, 0x3e027906
	v_mul_f32_e32 v52, v54, v52
	v_fma_f32 v54, |v56|, s26, 1.0
	v_rcp_f32_e32 v54, v54
	v_mul_f32_e32 v52, v53, v52
	v_max_f32_e32 v53, 0, v51
	v_fma_f32 v51, -|v51|, v52, v53
	v_mul_f32_e32 v52, v56, v56
	v_cvt_pk_bf16_f32 v50, v50, v51
	v_fmamk_f32 v51, v54, 0x3f07dc22, v211
	v_mul_f32_e32 v52, 0xbf38aa3b, v52
	v_fmaak_f32 v51, v54, v51, 0x3f35f0e3
	v_exp_f32_e32 v52, v52
	v_fmaak_f32 v51, v54, v51, 0xbe11a98e
	v_fma_f32 v53, |v57|, s26, 1.0
	v_fmaak_f32 v51, v54, v51, 0x3e027906
	v_rcp_f32_e32 v53, v53
	v_mul_f32_e32 v51, v54, v51
	v_mul_f32_e32 v51, v52, v51
	v_max_f32_e32 v52, 0, v56
	v_fma_f32 v51, -|v56|, v51, v52
	v_mul_f32_e32 v54, v57, v57
	v_mul_f32_e32 v54, 0xbf38aa3b, v54
	v_fmamk_f32 v52, v53, 0x3f07dc22, v211
	v_fmaak_f32 v52, v53, v52, 0x3f35f0e3
	v_exp_f32_e32 v54, v54
	v_fmaak_f32 v52, v53, v52, 0xbe11a98e
	v_fmaak_f32 v52, v53, v52, 0x3e027906
	v_mul_f32_e32 v52, v53, v52
	v_mul_f32_e32 v52, v54, v52
	v_mul_f32_e32 v54, 0x4b800000, v64
	v_cmp_gt_f32_e32 vcc, s89, v64
	v_max_f32_e32 v53, 0, v57
	v_fma_f32 v52, -|v57|, v52, v53
	v_cndmask_b32_e32 v54, v64, v54, vcc
	v_rsq_f32_e32 v54, v54
	v_cvt_pk_bf16_f32 v51, v51, v52
	global_store_dwordx4 v[66:67], v[48:51], off offset:64
	s_nop 1
	v_mul_f32_e32 v48, 0x45800000, v54
	v_cndmask_b32_e32 v48, v54, v48, vcc
	v_pk_mul_f32 v[44:45], v[44:45], v[48:49] op_sel_hi:[1,0]
	v_lshlrev_b64 v[50:51], 10, v[164:165]
	v_fma_f32 v49, |v44|, s26, 1.0
	v_rcp_f32_e32 v49, v49
	v_pk_mul_f32 v[52:53], v[42:43], v[48:49] op_sel_hi:[1,0]
	v_pk_mul_f32 v[42:43], v[40:41], v[48:49] op_sel_hi:[1,0]
	v_fmamk_f32 v40, v49, 0x3f07dc22, v211
	v_fmaak_f32 v40, v49, v40, 0x3f35f0e3
	v_mul_f32_e32 v41, v44, v44
	v_mul_f32_e32 v41, 0xbf38aa3b, v41
	v_fmaak_f32 v40, v49, v40, 0xbe11a98e
	v_exp_f32_e32 v41, v41
	v_fmaak_f32 v40, v49, v40, 0x3e027906
	v_pk_mul_f32 v[46:47], v[46:47], v[48:49] op_sel_hi:[1,0]
	v_mul_f32_e32 v40, v49, v40
	v_fma_f32 v49, |v45|, s26, 1.0
	v_rcp_f32_e32 v49, v49
	v_mul_f32_e32 v40, v41, v40
	v_max_f32_e32 v41, 0, v44
	v_fma_f32 v40, -|v44|, v40, v41
	v_fmamk_f32 v41, v49, 0x3f07dc22, v211
	v_mul_f32_e32 v44, v45, v45
	v_fmaak_f32 v41, v49, v41, 0x3f35f0e3
	v_mul_f32_e32 v44, 0xbf38aa3b, v44
	v_exp_f32_e32 v44, v44
	v_fmaak_f32 v41, v49, v41, 0xbe11a98e
	v_fmaak_f32 v41, v49, v41, 0x3e027906
	v_mul_f32_e32 v41, v49, v41
	v_fma_f32 v49, |v46|, s26, 1.0
	v_rcp_f32_e32 v49, v49
	v_mul_f32_e32 v41, v44, v41
	v_max_f32_e32 v44, 0, v45
	v_fma_f32 v41, -|v45|, v41, v44
	v_fma_f32 v45, |v47|, s26, 1.0
	v_rcp_f32_e32 v45, v45
	v_mul_f32_e32 v44, v46, v46
	v_cvt_pk_bf16_f32 v40, v40, v41
	v_fmamk_f32 v41, v49, 0x3f07dc22, v211
	v_mul_f32_e32 v44, 0xbf38aa3b, v44
	v_fmaak_f32 v41, v49, v41, 0x3f35f0e3
	v_exp_f32_e32 v44, v44
	v_fmaak_f32 v41, v49, v41, 0xbe11a98e
	v_fmaak_f32 v41, v49, v41, 0x3e027906
	v_mul_f32_e32 v41, v49, v41
	v_mul_f32_e32 v41, v44, v41
	v_max_f32_e32 v44, 0, v46
	v_fma_f32 v41, -|v46|, v41, v44
	v_mul_f32_e32 v46, v47, v47
	v_mul_f32_e32 v46, 0xbf38aa3b, v46
	v_fmamk_f32 v44, v45, 0x3f07dc22, v211
	v_fmaak_f32 v44, v45, v44, 0x3f35f0e3
	v_exp_f32_e32 v46, v46
	v_fmaak_f32 v44, v45, v44, 0xbe11a98e
	v_fmaak_f32 v44, v45, v44, 0x3e027906
	v_mul_f32_e32 v44, v45, v44
	v_mul_f32_e32 v44, v46, v44
	v_fma_f32 v46, |v42|, s26, 1.0
	v_rcp_f32_e32 v46, v46
	v_max_f32_e32 v45, 0, v47
	v_fma_f32 v44, -|v47|, v44, v45
	v_pk_mul_f32 v[36:37], v[36:37], v[48:49] op_sel_hi:[1,0]
	v_pk_mul_f32 v[38:39], v[38:39], v[48:49] op_sel_hi:[1,0]
	v_cvt_pk_bf16_f32 v41, v41, v44
	v_fmamk_f32 v44, v46, 0x3f07dc22, v211
	v_fmaak_f32 v44, v46, v44, 0x3f35f0e3
	v_mul_f32_e32 v45, v42, v42
	v_mul_f32_e32 v45, 0xbf38aa3b, v45
	v_fmaak_f32 v44, v46, v44, 0xbe11a98e
	v_exp_f32_e32 v45, v45
	v_fmaak_f32 v44, v46, v44, 0x3e027906
	v_mul_f32_e32 v44, v46, v44
	v_fma_f32 v46, |v43|, s26, 1.0
	v_rcp_f32_e32 v46, v46
	v_mul_f32_e32 v44, v45, v44
	v_max_f32_e32 v45, 0, v42
	v_fma_f32 v42, -|v42|, v44, v45
	v_fmamk_f32 v44, v46, 0x3f07dc22, v211
	v_mul_f32_e32 v45, v43, v43
	v_fmaak_f32 v44, v46, v44, 0x3f35f0e3
	v_mul_f32_e32 v45, 0xbf38aa3b, v45
	v_exp_f32_e32 v45, v45
	v_fmaak_f32 v44, v46, v44, 0xbe11a98e
	v_fmaak_f32 v44, v46, v44, 0x3e027906
	v_mul_f32_e32 v44, v46, v44
	v_fma_f32 v46, |v52|, s26, 1.0
	v_rcp_f32_e32 v46, v46
	v_mul_f32_e32 v44, v45, v44
	v_max_f32_e32 v45, 0, v43
	v_fma_f32 v43, -|v43|, v44, v45
	v_mul_f32_e32 v44, v52, v52
	v_cvt_pk_bf16_f32 v42, v42, v43
	v_fmamk_f32 v43, v46, 0x3f07dc22, v211
	v_mul_f32_e32 v44, 0xbf38aa3b, v44
	v_fmaak_f32 v43, v46, v43, 0x3f35f0e3
	v_exp_f32_e32 v44, v44
	v_fmaak_f32 v43, v46, v43, 0xbe11a98e
	v_fma_f32 v45, |v53|, s26, 1.0
	v_fmaak_f32 v43, v46, v43, 0x3e027906
	v_rcp_f32_e32 v45, v45
	v_mul_f32_e32 v43, v46, v43
	v_mul_f32_e32 v43, v44, v43
	v_max_f32_e32 v44, 0, v52
	v_fma_f32 v43, -|v52|, v43, v44
	v_mul_f32_e32 v46, v53, v53
	v_mul_f32_e32 v46, 0xbf38aa3b, v46
	v_fmamk_f32 v44, v45, 0x3f07dc22, v211
	v_fmaak_f32 v44, v45, v44, 0x3f35f0e3
	v_exp_f32_e32 v46, v46
	v_fmaak_f32 v44, v45, v44, 0xbe11a98e
	v_fmaak_f32 v44, v45, v44, 0x3e027906
	v_mul_f32_e32 v44, v45, v44
	v_mul_f32_e32 v44, v46, v44
	v_max_f32_e32 v45, 0, v53
	v_fma_f32 v44, -|v53|, v44, v45
	v_cvt_pk_bf16_f32 v43, v43, v44
	v_lshl_add_u64 v[44:45], s[96:97], 0, v[50:51]
	v_lshl_add_u64 v[44:45], v[44:45], 0, s[98:99]
	v_lshl_add_u64 v[44:45], v[44:45], 0, v[144:145]
	global_store_dwordx4 v[44:45], v[40:43], off
	s_nop 0
	v_fma_f32 v40, |v36|, s26, 1.0
	v_rcp_f32_e32 v42, v40
	v_pk_mul_f32 v[40:41], v[34:35], v[48:49] op_sel_hi:[1,0]
	v_pk_mul_f32 v[34:35], v[32:33], v[48:49] op_sel_hi:[1,0]
	v_mul_f32_e32 v33, v36, v36
	v_fmamk_f32 v32, v42, 0x3f07dc22, v211
	v_fmaak_f32 v32, v42, v32, 0x3f35f0e3
	v_mul_f32_e32 v33, 0xbf38aa3b, v33
	v_fmaak_f32 v32, v42, v32, 0xbe11a98e
	v_exp_f32_e32 v33, v33
	v_fmaak_f32 v32, v42, v32, 0x3e027906
	v_mul_f32_e32 v32, v42, v32
	v_fma_f32 v42, |v37|, s26, 1.0
	v_rcp_f32_e32 v42, v42
	v_mul_f32_e32 v32, v33, v32
	v_max_f32_e32 v33, 0, v36
	v_fma_f32 v32, -|v36|, v32, v33
	v_fmamk_f32 v33, v42, 0x3f07dc22, v211
	v_mul_f32_e32 v36, v37, v37
	v_fmaak_f32 v33, v42, v33, 0x3f35f0e3
	v_mul_f32_e32 v36, 0xbf38aa3b, v36
	v_exp_f32_e32 v36, v36
	v_fmaak_f32 v33, v42, v33, 0xbe11a98e
	v_fmaak_f32 v33, v42, v33, 0x3e027906
	v_mul_f32_e32 v33, v42, v33
	v_fma_f32 v42, |v38|, s26, 1.0
	v_rcp_f32_e32 v42, v42
	v_mul_f32_e32 v33, v36, v33
	v_max_f32_e32 v36, 0, v37
	v_fma_f32 v33, -|v37|, v33, v36
	v_fma_f32 v37, |v39|, s26, 1.0
	v_rcp_f32_e32 v37, v37
	v_mul_f32_e32 v36, v38, v38
	v_cvt_pk_bf16_f32 v32, v32, v33
	v_fmamk_f32 v33, v42, 0x3f07dc22, v211
	v_mul_f32_e32 v36, 0xbf38aa3b, v36
	v_fmaak_f32 v33, v42, v33, 0x3f35f0e3
	v_exp_f32_e32 v36, v36
	v_fmaak_f32 v33, v42, v33, 0xbe11a98e
	v_fmaak_f32 v33, v42, v33, 0x3e027906
	v_mul_f32_e32 v33, v42, v33
	v_mul_f32_e32 v33, v36, v33
	v_max_f32_e32 v36, 0, v38
	v_fma_f32 v33, -|v38|, v33, v36
	v_mul_f32_e32 v38, v39, v39
	v_mul_f32_e32 v38, 0xbf38aa3b, v38
	v_fmamk_f32 v36, v37, 0x3f07dc22, v211
	v_fmaak_f32 v36, v37, v36, 0x3f35f0e3
	v_exp_f32_e32 v38, v38
	v_fmaak_f32 v36, v37, v36, 0xbe11a98e
	v_fmaak_f32 v36, v37, v36, 0x3e027906
	v_mul_f32_e32 v36, v37, v36
	v_mul_f32_e32 v36, v38, v36
	v_fma_f32 v38, |v34|, s26, 1.0
	v_rcp_f32_e32 v38, v38
	v_max_f32_e32 v37, 0, v39
	v_fma_f32 v36, -|v39|, v36, v37
	v_cvt_pk_bf16_f32 v33, v33, v36
	v_fmamk_f32 v36, v38, 0x3f07dc22, v211
	v_fmaak_f32 v36, v38, v36, 0x3f35f0e3
	v_mul_f32_e32 v37, v34, v34
	v_mul_f32_e32 v37, 0xbf38aa3b, v37
	v_fmaak_f32 v36, v38, v36, 0xbe11a98e
	v_exp_f32_e32 v37, v37
	v_fmaak_f32 v36, v38, v36, 0x3e027906
	v_mul_f32_e32 v36, v38, v36
	v_fma_f32 v38, |v35|, s26, 1.0
	v_rcp_f32_e32 v38, v38
	v_mul_f32_e32 v36, v37, v36
	v_max_f32_e32 v37, 0, v34
	v_fma_f32 v34, -|v34|, v36, v37
	v_fmamk_f32 v36, v38, 0x3f07dc22, v211
	v_mul_f32_e32 v37, v35, v35
	v_fmaak_f32 v36, v38, v36, 0x3f35f0e3
	v_mul_f32_e32 v37, 0xbf38aa3b, v37
	v_exp_f32_e32 v37, v37
	v_fmaak_f32 v36, v38, v36, 0xbe11a98e
	v_fmaak_f32 v36, v38, v36, 0x3e027906
	v_mul_f32_e32 v36, v38, v36
	v_fma_f32 v38, |v40|, s26, 1.0
	v_rcp_f32_e32 v38, v38
	v_mul_f32_e32 v36, v37, v36
	v_max_f32_e32 v37, 0, v35
	v_fma_f32 v35, -|v35|, v36, v37
	v_mul_f32_e32 v36, v40, v40
	v_cvt_pk_bf16_f32 v34, v34, v35
	v_fmamk_f32 v35, v38, 0x3f07dc22, v211
	v_mul_f32_e32 v36, 0xbf38aa3b, v36
	v_fmaak_f32 v35, v38, v35, 0x3f35f0e3
	v_exp_f32_e32 v36, v36
	v_fmaak_f32 v35, v38, v35, 0xbe11a98e
	v_fma_f32 v37, |v41|, s26, 1.0
	v_fmaak_f32 v35, v38, v35, 0x3e027906
	v_rcp_f32_e32 v37, v37
	v_mul_f32_e32 v35, v38, v35
	v_mul_f32_e32 v35, v36, v35
	v_max_f32_e32 v36, 0, v40
	v_fma_f32 v35, -|v40|, v35, v36
	v_mul_f32_e32 v38, v41, v41
	v_mul_f32_e32 v38, 0xbf38aa3b, v38
	v_fmamk_f32 v36, v37, 0x3f07dc22, v211
	v_fmaak_f32 v36, v37, v36, 0x3f35f0e3
	v_exp_f32_e32 v38, v38
	v_fmaak_f32 v36, v37, v36, 0xbe11a98e
	v_fmaak_f32 v36, v37, v36, 0x3e027906
	v_mul_f32_e32 v36, v37, v36
	v_mul_f32_e32 v36, v38, v36
	v_mul_f32_e32 v37, v41, v36
	v_fma_f32 v36, -v41, v36, v41
	v_cmp_gt_f32_e32 vcc, 0, v41
	s_nop 1
	v_cndmask_b32_e32 v36, v36, v37, vcc
	v_cvt_pk_bf16_f32 v35, v35, v36
	global_store_dwordx4 v[44:45], v[32:35], off offset:64
	s_nop 1
	v_ffbh_u32_e32 v32, v163
	v_min_u32_e32 v34, 32, v32
	v_lshlrev_b64 v[32:33], v34, v[162:163]
	v_min_u32_e32 v32, 1, v32
	v_or_b32_e32 v32, v33, v32
	v_cvt_f32_u32_e32 v35, v32
	v_ffbh_u32_e32 v32, v161
	v_min_u32_e32 v36, 32, v32
	v_lshlrev_b64 v[32:33], v36, v[160:161]
	v_min_u32_e32 v32, 1, v32
	v_or_b32_e32 v32, v33, v32
	v_cvt_f32_u32_e32 v32, v32
	v_sub_u32_e32 v33, 32, v34
	v_sub_u32_e32 v34, 32, v36
	v_ldexp_f32 v33, v35, v33
	v_ldexp_f32 v32, v32, v34
	v_pk_mul_f32 v[32:33], v[32:33], s[30:31] op_sel_hi:[1,0]
	v_lshlrev_b64 v[34:35], 10, v[158:159]
	v_pk_fma_f32 v[32:33], v[32:33], s[2:3], v[128:129] op_sel_hi:[1,0,0]
	v_lshl_add_u64 v[34:35], s[96:97], 0, v[34:35]
	v_mul_f32_e32 v36, 0x4b800000, v33
	v_cmp_gt_f32_e32 vcc, s89, v33
	v_lshl_add_u64 v[34:35], v[34:35], 0, s[98:99]
	v_lshl_add_u64 v[34:35], v[34:35], 0, v[144:145]
	v_cndmask_b32_e32 v33, v33, v36, vcc
	v_rsq_f32_e32 v33, v33
	s_nop 0
	v_mul_f32_e32 v36, 0x45800000, v33
	v_cndmask_b32_e32 v36, v33, v36, vcc
	v_pk_mul_f32 v[28:29], v[28:29], v[36:37] op_sel_hi:[1,0]
	v_pk_mul_f32 v[38:39], v[26:27], v[36:37] op_sel_hi:[1,0]
	v_fma_f32 v33, |v28|, s26, 1.0
	v_rcp_f32_e32 v33, v33
	v_pk_mul_f32 v[26:27], v[24:25], v[36:37] op_sel_hi:[1,0]
	v_mul_f32_e32 v25, v28, v28
	v_mul_f32_e32 v25, 0xbf38aa3b, v25
	v_fmamk_f32 v24, v33, 0x3f07dc22, v211
	v_fmaak_f32 v24, v33, v24, 0x3f35f0e3
	v_fmaak_f32 v24, v33, v24, 0xbe11a98e
	v_exp_f32_e32 v25, v25
	v_fmaak_f32 v24, v33, v24, 0x3e027906
	v_mul_f32_e32 v24, v33, v24
	v_fma_f32 v33, |v29|, s26, 1.0
	v_rcp_f32_e32 v33, v33
	v_mul_f32_e32 v24, v25, v24
	v_max_f32_e32 v25, 0, v28
	v_fma_f32 v24, -|v28|, v24, v25
	v_mul_f32_e32 v28, v29, v29
	v_mul_f32_e32 v28, 0xbf38aa3b, v28
	v_fmamk_f32 v25, v33, 0x3f07dc22, v211
	v_fmaak_f32 v25, v33, v25, 0x3f35f0e3
	v_exp_f32_e32 v28, v28
	v_fmaak_f32 v25, v33, v25, 0xbe11a98e
	v_pk_mul_f32 v[30:31], v[30:31], v[36:37] op_sel_hi:[1,0]
	v_fmaak_f32 v25, v33, v25, 0x3e027906
	v_mul_f32_e32 v25, v33, v25
	v_fma_f32 v33, |v30|, s26, 1.0
	v_rcp_f32_e32 v33, v33
	v_mul_f32_e32 v25, v28, v25
	v_max_f32_e32 v28, 0, v29
	v_fma_f32 v25, -|v29|, v25, v28
	v_fma_f32 v29, |v31|, s26, 1.0
	v_rcp_f32_e32 v29, v29
	v_mul_f32_e32 v28, v30, v30
	v_cvt_pk_bf16_f32 v24, v24, v25
	v_fmamk_f32 v25, v33, 0x3f07dc22, v211
	v_mul_f32_e32 v28, 0xbf38aa3b, v28
	v_fmaak_f32 v25, v33, v25, 0x3f35f0e3
	v_exp_f32_e32 v28, v28
	v_fmaak_f32 v25, v33, v25, 0xbe11a98e
	v_fmaak_f32 v25, v33, v25, 0x3e027906
	v_mul_f32_e32 v25, v33, v25
	v_mul_f32_e32 v25, v28, v25
	v_max_f32_e32 v28, 0, v30
	v_fma_f32 v25, -|v30|, v25, v28
	v_mul_f32_e32 v30, v31, v31
	v_mul_f32_e32 v30, 0xbf38aa3b, v30
	v_fmamk_f32 v28, v29, 0x3f07dc22, v211
	v_fmaak_f32 v28, v29, v28, 0x3f35f0e3
	v_exp_f32_e32 v30, v30
	v_fmaak_f32 v28, v29, v28, 0xbe11a98e
	v_fmaak_f32 v28, v29, v28, 0x3e027906
	v_mul_f32_e32 v28, v29, v28
	v_mul_f32_e32 v28, v30, v28
	v_fma_f32 v30, |v26|, s26, 1.0
	v_rcp_f32_e32 v30, v30
	v_max_f32_e32 v29, 0, v31
	v_fma_f32 v28, -|v31|, v28, v29
	v_pk_mul_f32 v[20:21], v[20:21], v[36:37] op_sel_hi:[1,0]
	v_pk_mul_f32 v[22:23], v[22:23], v[36:37] op_sel_hi:[1,0]
	v_cvt_pk_bf16_f32 v25, v25, v28
	v_fmamk_f32 v28, v30, 0x3f07dc22, v211
	v_fmaak_f32 v28, v30, v28, 0x3f35f0e3
	v_mul_f32_e32 v29, v26, v26
	v_mul_f32_e32 v29, 0xbf38aa3b, v29
	v_fmaak_f32 v28, v30, v28, 0xbe11a98e
	v_exp_f32_e32 v29, v29
	v_fmaak_f32 v28, v30, v28, 0x3e027906
	v_mul_f32_e32 v28, v30, v28
	v_fma_f32 v30, |v27|, s26, 1.0
	v_rcp_f32_e32 v30, v30
	v_mul_f32_e32 v28, v29, v28
	v_max_f32_e32 v29, 0, v26
	v_fma_f32 v26, -|v26|, v28, v29
	v_fmamk_f32 v28, v30, 0x3f07dc22, v211
	v_mul_f32_e32 v29, v27, v27
	v_fmaak_f32 v28, v30, v28, 0x3f35f0e3
	v_mul_f32_e32 v29, 0xbf38aa3b, v29
	v_exp_f32_e32 v29, v29
	v_fmaak_f32 v28, v30, v28, 0xbe11a98e
	v_fmaak_f32 v28, v30, v28, 0x3e027906
	v_mul_f32_e32 v28, v30, v28
	v_fma_f32 v30, |v38|, s26, 1.0
	v_rcp_f32_e32 v30, v30
	v_mul_f32_e32 v28, v29, v28
	v_max_f32_e32 v29, 0, v27
	v_fma_f32 v27, -|v27|, v28, v29
	v_mul_f32_e32 v28, v38, v38
	v_cvt_pk_bf16_f32 v26, v26, v27
	v_fmamk_f32 v27, v30, 0x3f07dc22, v211
	v_mul_f32_e32 v28, 0xbf38aa3b, v28
	v_fmaak_f32 v27, v30, v27, 0x3f35f0e3
	v_exp_f32_e32 v28, v28
	v_fmaak_f32 v27, v30, v27, 0xbe11a98e
	v_fma_f32 v29, |v39|, s26, 1.0
	v_fmaak_f32 v27, v30, v27, 0x3e027906
	v_rcp_f32_e32 v29, v29
	v_mul_f32_e32 v27, v30, v27
	v_mul_f32_e32 v27, v28, v27
	v_max_f32_e32 v28, 0, v38
	v_fma_f32 v27, -|v38|, v27, v28
	v_mul_f32_e32 v30, v39, v39
	v_mul_f32_e32 v30, 0xbf38aa3b, v30
	v_fmamk_f32 v28, v29, 0x3f07dc22, v211
	v_fmaak_f32 v28, v29, v28, 0x3f35f0e3
	v_exp_f32_e32 v30, v30
	v_fmaak_f32 v28, v29, v28, 0xbe11a98e
	v_fmaak_f32 v28, v29, v28, 0x3e027906
	v_mul_f32_e32 v28, v29, v28
	v_mul_f32_e32 v28, v30, v28
	v_max_f32_e32 v29, 0, v39
	v_fma_f32 v28, -|v39|, v28, v29
	v_cvt_pk_bf16_f32 v27, v27, v28
	global_store_dwordx4 v[34:35], v[24:27], off
	s_nop 0
	v_fma_f32 v24, |v20|, s26, 1.0
	v_rcp_f32_e32 v26, v24
	v_pk_mul_f32 v[24:25], v[18:19], v[36:37] op_sel_hi:[1,0]
	v_pk_mul_f32 v[18:19], v[16:17], v[36:37] op_sel_hi:[1,0]
	v_mul_f32_e32 v17, v20, v20
	v_fmamk_f32 v16, v26, 0x3f07dc22, v211
	v_fmaak_f32 v16, v26, v16, 0x3f35f0e3
	v_mul_f32_e32 v17, 0xbf38aa3b, v17
	v_fmaak_f32 v16, v26, v16, 0xbe11a98e
	v_exp_f32_e32 v17, v17
	v_fmaak_f32 v16, v26, v16, 0x3e027906
	v_mul_f32_e32 v16, v26, v16
	v_fma_f32 v26, |v21|, s26, 1.0
	v_rcp_f32_e32 v26, v26
	v_mul_f32_e32 v16, v17, v16
	v_max_f32_e32 v17, 0, v20
	v_fma_f32 v16, -|v20|, v16, v17
	v_fmamk_f32 v17, v26, 0x3f07dc22, v211
	v_mul_f32_e32 v20, v21, v21
	v_fmaak_f32 v17, v26, v17, 0x3f35f0e3
	v_mul_f32_e32 v20, 0xbf38aa3b, v20
	v_exp_f32_e32 v20, v20
	v_fmaak_f32 v17, v26, v17, 0xbe11a98e
	v_fmaak_f32 v17, v26, v17, 0x3e027906
	v_mul_f32_e32 v17, v26, v17
	v_fma_f32 v26, |v22|, s26, 1.0
	v_rcp_f32_e32 v26, v26
	v_mul_f32_e32 v17, v20, v17
	v_max_f32_e32 v20, 0, v21
	v_fma_f32 v17, -|v21|, v17, v20
	v_fma_f32 v21, |v23|, s26, 1.0
	v_rcp_f32_e32 v21, v21
	v_mul_f32_e32 v20, v22, v22
	v_cvt_pk_bf16_f32 v16, v16, v17
	v_fmamk_f32 v17, v26, 0x3f07dc22, v211
	v_mul_f32_e32 v20, 0xbf38aa3b, v20
	v_fmaak_f32 v17, v26, v17, 0x3f35f0e3
	v_exp_f32_e32 v20, v20
	v_fmaak_f32 v17, v26, v17, 0xbe11a98e
	v_fmaak_f32 v17, v26, v17, 0x3e027906
	v_mul_f32_e32 v17, v26, v17
	v_mul_f32_e32 v17, v20, v17
	v_max_f32_e32 v20, 0, v22
	v_fma_f32 v17, -|v22|, v17, v20
	v_mul_f32_e32 v22, v23, v23
	v_mul_f32_e32 v22, 0xbf38aa3b, v22
	v_fmamk_f32 v20, v21, 0x3f07dc22, v211
	v_fmaak_f32 v20, v21, v20, 0x3f35f0e3
	v_exp_f32_e32 v22, v22
	v_fmaak_f32 v20, v21, v20, 0xbe11a98e
	v_fmaak_f32 v20, v21, v20, 0x3e027906
	v_mul_f32_e32 v20, v21, v20
	v_mul_f32_e32 v20, v22, v20
	v_fma_f32 v22, |v18|, s26, 1.0
	v_rcp_f32_e32 v22, v22
	v_max_f32_e32 v21, 0, v23
	v_fma_f32 v20, -|v23|, v20, v21
	s_nop 0
	v_cvt_pk_bf16_f32 v17, v17, v20
	v_fmamk_f32 v20, v22, 0x3f07dc22, v211
	v_fmaak_f32 v20, v22, v20, 0x3f35f0e3
	v_mul_f32_e32 v21, v18, v18
	v_mul_f32_e32 v21, 0xbf38aa3b, v21
	v_fmaak_f32 v20, v22, v20, 0xbe11a98e
	v_exp_f32_e32 v21, v21
	v_fmaak_f32 v20, v22, v20, 0x3e027906
	v_mul_f32_e32 v20, v22, v20
	v_fma_f32 v22, |v19|, s26, 1.0
	v_rcp_f32_e32 v22, v22
	v_mul_f32_e32 v20, v21, v20
	v_max_f32_e32 v21, 0, v18
	v_fma_f32 v18, -|v18|, v20, v21
	v_fmamk_f32 v20, v22, 0x3f07dc22, v211
	v_mul_f32_e32 v21, v19, v19
	v_fmaak_f32 v20, v22, v20, 0x3f35f0e3
	v_mul_f32_e32 v21, 0xbf38aa3b, v21
	v_exp_f32_e32 v21, v21
	v_fmaak_f32 v20, v22, v20, 0xbe11a98e
	v_fmaak_f32 v20, v22, v20, 0x3e027906
	v_mul_f32_e32 v20, v22, v20
	v_fma_f32 v22, |v24|, s26, 1.0
	v_rcp_f32_e32 v22, v22
	v_mul_f32_e32 v20, v21, v20
	v_max_f32_e32 v21, 0, v19
	v_fma_f32 v19, -|v19|, v20, v21
	v_mul_f32_e32 v20, v24, v24
	v_cvt_pk_bf16_f32 v18, v18, v19
	v_fmamk_f32 v19, v22, 0x3f07dc22, v211
	v_mul_f32_e32 v20, 0xbf38aa3b, v20
	v_fmaak_f32 v19, v22, v19, 0x3f35f0e3
	v_exp_f32_e32 v20, v20
	v_fmaak_f32 v19, v22, v19, 0xbe11a98e
	v_fma_f32 v21, |v25|, s26, 1.0
	v_fmaak_f32 v19, v22, v19, 0x3e027906
	v_rcp_f32_e32 v21, v21
	v_mul_f32_e32 v19, v22, v19
	v_mul_f32_e32 v19, v20, v19
	v_max_f32_e32 v20, 0, v24
	v_fma_f32 v19, -|v24|, v19, v20
	v_mul_f32_e32 v22, v25, v25
	v_mul_f32_e32 v22, 0xbf38aa3b, v22
	v_fmamk_f32 v20, v21, 0x3f07dc22, v211
	v_fmaak_f32 v20, v21, v20, 0x3f35f0e3
	v_exp_f32_e32 v22, v22
	v_fmaak_f32 v20, v21, v20, 0xbe11a98e
	v_fmaak_f32 v20, v21, v20, 0x3e027906
	v_mul_f32_e32 v20, v21, v20
	v_mul_f32_e32 v20, v22, v20
	v_mul_f32_e32 v22, 0x4b800000, v32
	v_cmp_gt_f32_e32 vcc, s89, v32
	v_max_f32_e32 v21, 0, v25
	v_fma_f32 v20, -|v25|, v20, v21
	v_cndmask_b32_e32 v22, v32, v22, vcc
	v_rsq_f32_e32 v22, v22
	v_cvt_pk_bf16_f32 v19, v19, v20
	global_store_dwordx4 v[34:35], v[16:19], off offset:64
	s_nop 1
	v_mul_f32_e32 v16, 0x45800000, v22
	v_cndmask_b32_e32 v16, v22, v16, vcc
	v_pk_mul_f32 v[12:13], v[12:13], v[16:17] op_sel_hi:[1,0]
	v_lshlrev_b64 v[18:19], 10, v[156:157]
	v_fma_f32 v17, |v12|, s26, 1.0
	v_rcp_f32_e32 v17, v17
	v_pk_mul_f32 v[20:21], v[10:11], v[16:17] op_sel_hi:[1,0]
	v_pk_mul_f32 v[10:11], v[8:9], v[16:17] op_sel_hi:[1,0]
	v_fmamk_f32 v8, v17, 0x3f07dc22, v211
	v_fmaak_f32 v8, v17, v8, 0x3f35f0e3
	v_mul_f32_e32 v9, v12, v12
	v_mul_f32_e32 v9, 0xbf38aa3b, v9
	v_fmaak_f32 v8, v17, v8, 0xbe11a98e
	v_exp_f32_e32 v9, v9
	v_fmaak_f32 v8, v17, v8, 0x3e027906
	v_pk_mul_f32 v[14:15], v[14:15], v[16:17] op_sel_hi:[1,0]
	v_mul_f32_e32 v8, v17, v8
	v_fma_f32 v17, |v13|, s26, 1.0
	v_rcp_f32_e32 v17, v17
	v_mul_f32_e32 v8, v9, v8
	v_max_f32_e32 v9, 0, v12
	v_fma_f32 v8, -|v12|, v8, v9
	v_fmamk_f32 v9, v17, 0x3f07dc22, v211
	v_mul_f32_e32 v12, v13, v13
	v_fmaak_f32 v9, v17, v9, 0x3f35f0e3
	v_mul_f32_e32 v12, 0xbf38aa3b, v12
	v_exp_f32_e32 v12, v12
	v_fmaak_f32 v9, v17, v9, 0xbe11a98e
	v_fmaak_f32 v9, v17, v9, 0x3e027906
	v_mul_f32_e32 v9, v17, v9
	v_fma_f32 v17, |v14|, s26, 1.0
	v_rcp_f32_e32 v17, v17
	v_mul_f32_e32 v9, v12, v9
	v_max_f32_e32 v12, 0, v13
	v_fma_f32 v9, -|v13|, v9, v12
	v_fma_f32 v13, |v15|, s26, 1.0
	v_rcp_f32_e32 v13, v13
	v_mul_f32_e32 v12, v14, v14
	v_cvt_pk_bf16_f32 v8, v8, v9
	v_fmamk_f32 v9, v17, 0x3f07dc22, v211
	v_mul_f32_e32 v12, 0xbf38aa3b, v12
	v_fmaak_f32 v9, v17, v9, 0x3f35f0e3
	v_exp_f32_e32 v12, v12
	v_fmaak_f32 v9, v17, v9, 0xbe11a98e
	v_fmaak_f32 v9, v17, v9, 0x3e027906
	v_mul_f32_e32 v9, v17, v9
	v_mul_f32_e32 v9, v12, v9
	v_max_f32_e32 v12, 0, v14
	v_fma_f32 v9, -|v14|, v9, v12
	v_mul_f32_e32 v14, v15, v15
	v_mul_f32_e32 v14, 0xbf38aa3b, v14
	v_fmamk_f32 v12, v13, 0x3f07dc22, v211
	v_fmaak_f32 v12, v13, v12, 0x3f35f0e3
	v_exp_f32_e32 v14, v14
	v_fmaak_f32 v12, v13, v12, 0xbe11a98e
	v_fmaak_f32 v12, v13, v12, 0x3e027906
	v_mul_f32_e32 v12, v13, v12
	v_mul_f32_e32 v12, v14, v12
	v_fma_f32 v14, |v10|, s26, 1.0
	v_rcp_f32_e32 v14, v14
	v_max_f32_e32 v13, 0, v15
	v_fma_f32 v12, -|v15|, v12, v13
	v_pk_mul_f32 v[4:5], v[4:5], v[16:17] op_sel_hi:[1,0]
	v_pk_mul_f32 v[6:7], v[6:7], v[16:17] op_sel_hi:[1,0]
	v_cvt_pk_bf16_f32 v9, v9, v12
	v_fmamk_f32 v12, v14, 0x3f07dc22, v211
	v_fmaak_f32 v12, v14, v12, 0x3f35f0e3
	v_mul_f32_e32 v13, v10, v10
	v_mul_f32_e32 v13, 0xbf38aa3b, v13
	v_fmaak_f32 v12, v14, v12, 0xbe11a98e
	v_exp_f32_e32 v13, v13
	v_fmaak_f32 v12, v14, v12, 0x3e027906
	v_mul_f32_e32 v12, v14, v12
	v_fma_f32 v14, |v11|, s26, 1.0
	v_rcp_f32_e32 v14, v14
	v_mul_f32_e32 v12, v13, v12
	v_max_f32_e32 v13, 0, v10
	v_fma_f32 v10, -|v10|, v12, v13
	v_pk_mul_f32 v[0:1], v[0:1], v[16:17] op_sel_hi:[1,0]
	v_pk_mul_f32 v[2:3], v[2:3], v[16:17] op_sel_hi:[1,0]
	v_fmamk_f32 v12, v14, 0x3f07dc22, v211
	v_mul_f32_e32 v13, v11, v11
	v_fmaak_f32 v12, v14, v12, 0x3f35f0e3
	v_mul_f32_e32 v13, 0xbf38aa3b, v13
	v_exp_f32_e32 v13, v13
	v_fmaak_f32 v12, v14, v12, 0xbe11a98e
	v_fmaak_f32 v12, v14, v12, 0x3e027906
	v_mul_f32_e32 v12, v14, v12
	v_fma_f32 v14, |v20|, s26, 1.0
	v_rcp_f32_e32 v14, v14
	v_mul_f32_e32 v12, v13, v12
	v_max_f32_e32 v13, 0, v11
	v_fma_f32 v11, -|v11|, v12, v13
	v_mul_f32_e32 v12, v20, v20
	v_cvt_pk_bf16_f32 v10, v10, v11
	v_fmamk_f32 v11, v14, 0x3f07dc22, v211
	v_mul_f32_e32 v12, 0xbf38aa3b, v12
	v_fmaak_f32 v11, v14, v11, 0x3f35f0e3
	v_exp_f32_e32 v12, v12
	v_fmaak_f32 v11, v14, v11, 0xbe11a98e
	v_fma_f32 v13, |v21|, s26, 1.0
	v_fmaak_f32 v11, v14, v11, 0x3e027906
	v_rcp_f32_e32 v13, v13
	v_mul_f32_e32 v11, v14, v11
	v_mul_f32_e32 v11, v12, v11
	v_max_f32_e32 v12, 0, v20
	v_fma_f32 v11, -|v20|, v11, v12
	v_mul_f32_e32 v14, v21, v21
	v_mul_f32_e32 v14, 0xbf38aa3b, v14
	v_fmamk_f32 v12, v13, 0x3f07dc22, v211
	v_fmaak_f32 v12, v13, v12, 0x3f35f0e3
	v_exp_f32_e32 v14, v14
	v_fmaak_f32 v12, v13, v12, 0xbe11a98e
	v_fmaak_f32 v12, v13, v12, 0x3e027906
	v_mul_f32_e32 v12, v13, v12
	v_mul_f32_e32 v12, v14, v12
	v_max_f32_e32 v13, 0, v21
	v_fma_f32 v12, -|v21|, v12, v13
	v_cvt_pk_bf16_f32 v11, v11, v12
	v_lshl_add_u64 v[12:13], s[96:97], 0, v[18:19]
	v_lshl_add_u64 v[12:13], v[12:13], 0, s[98:99]
	v_lshl_add_u64 v[206:207], v[12:13], 0, v[144:145]
	global_store_dwordx4 v[206:207], v[8:11], off
	s_nop 0
	v_fma_f32 v8, |v4|, s26, 1.0
	v_rcp_f32_e32 v8, v8
	v_mul_f32_e32 v10, v4, v4
	v_mul_f32_e32 v10, 0xbf38aa3b, v10
	v_exp_f32_e32 v10, v10
	v_fmamk_f32 v9, v8, 0x3f07dc22, v211
	v_fmaak_f32 v9, v8, v9, 0x3f35f0e3
	v_fmaak_f32 v9, v8, v9, 0xbe11a98e
	v_fmaak_f32 v9, v8, v9, 0x3e027906
	v_mul_f32_e32 v8, v8, v9
	v_mul_f32_e32 v8, v10, v8
	v_fma_f32 v10, |v5|, s26, 1.0
	v_rcp_f32_e32 v10, v10
	v_max_f32_e32 v9, 0, v4
	v_fma_f32 v4, -|v4|, v8, v9
	v_mul_f32_e32 v9, v5, v5
	v_fmamk_f32 v8, v10, 0x3f07dc22, v211
	v_mul_f32_e32 v9, 0xbf38aa3b, v9
	v_fmaak_f32 v8, v10, v8, 0x3f35f0e3
	v_exp_f32_e32 v9, v9
	v_fmaak_f32 v8, v10, v8, 0xbe11a98e
	v_fmaak_f32 v8, v10, v8, 0x3e027906
	v_mul_f32_e32 v8, v10, v8
	v_fma_f32 v10, |v6|, s26, 1.0
	v_mul_f32_e32 v8, v9, v8
	v_rcp_f32_e32 v10, v10
	v_max_f32_e32 v9, 0, v5
	v_fma_f32 v5, -|v5|, v8, v9
	v_cvt_pk_bf16_f32 v128, v4, v5
	v_mul_f32_e32 v5, v6, v6
	v_fmamk_f32 v4, v10, 0x3f07dc22, v211
	v_mul_f32_e32 v5, 0xbf38aa3b, v5
	v_fmaak_f32 v4, v10, v4, 0x3f35f0e3
	v_exp_f32_e32 v5, v5
	v_fmaak_f32 v4, v10, v4, 0xbe11a98e
	v_fma_f32 v8, |v7|, s26, 1.0
	v_fmaak_f32 v4, v10, v4, 0x3e027906
	v_rcp_f32_e32 v8, v8
	v_mul_f32_e32 v4, v10, v4
	v_mul_f32_e32 v4, v5, v4
	v_max_f32_e32 v5, 0, v6
	v_fma_f32 v4, -|v6|, v4, v5
	v_mul_f32_e32 v6, v7, v7
	v_mul_f32_e32 v6, 0xbf38aa3b, v6
	v_fmamk_f32 v5, v8, 0x3f07dc22, v211
	v_fmaak_f32 v5, v8, v5, 0x3f35f0e3
	v_exp_f32_e32 v6, v6
	v_fmaak_f32 v5, v8, v5, 0xbe11a98e
	v_fmaak_f32 v5, v8, v5, 0x3e027906
	v_mul_f32_e32 v5, v8, v5
	v_fma_f32 v8, |v0|, s26, 1.0
	v_mul_f32_e32 v5, v6, v5
	v_rcp_f32_e32 v8, v8
	v_max_f32_e32 v6, 0, v7
	v_fma_f32 v5, -|v7|, v5, v6
	v_cvt_pk_bf16_f32 v129, v4, v5
	v_mul_f32_e32 v5, v0, v0
	v_fmamk_f32 v4, v8, 0x3f07dc22, v211
	v_mul_f32_e32 v5, 0xbf38aa3b, v5
	v_fmaak_f32 v4, v8, v4, 0x3f35f0e3
	v_exp_f32_e32 v5, v5
	v_fmaak_f32 v4, v8, v4, 0xbe11a98e
	v_fmaak_f32 v4, v8, v4, 0x3e027906
	v_fma_f32 v6, |v1|, s26, 1.0
	v_mul_f32_e32 v4, v8, v4
	v_rcp_f32_e32 v6, v6
	v_mul_f32_e32 v4, v5, v4
	v_max_f32_e32 v5, 0, v0
	v_fma_f32 v0, -|v0|, v4, v5
	v_mul_f32_e32 v5, v1, v1
	v_fmamk_f32 v4, v6, 0x3f07dc22, v211
	v_mul_f32_e32 v5, 0xbf38aa3b, v5
	v_fmaak_f32 v4, v6, v4, 0x3f35f0e3
	v_exp_f32_e32 v5, v5
	v_fmaak_f32 v4, v6, v4, 0xbe11a98e
	v_fmaak_f32 v4, v6, v4, 0x3e027906
	v_mul_f32_e32 v4, v6, v4
	v_fma_f32 v6, |v2|, s26, 1.0
	v_mul_f32_e32 v4, v5, v4
	v_rcp_f32_e32 v6, v6
	v_max_f32_e32 v5, 0, v1
	v_fma_f32 v1, -|v1|, v4, v5
	v_cvt_pk_bf16_f32 v130, v0, v1
	v_mul_f32_e32 v1, v2, v2
	v_fmamk_f32 v0, v6, 0x3f07dc22, v211
	v_mul_f32_e32 v1, 0xbf38aa3b, v1
	v_fmaak_f32 v0, v6, v0, 0x3f35f0e3
	v_exp_f32_e32 v1, v1
	v_fmaak_f32 v0, v6, v0, 0xbe11a98e
	v_fma_f32 v4, |v3|, s26, 1.0
	v_fmaak_f32 v0, v6, v0, 0x3e027906
	v_rcp_f32_e32 v4, v4
	v_mul_f32_e32 v0, v6, v0
	v_mul_f32_e32 v0, v1, v0
	v_max_f32_e32 v1, 0, v2
	v_fma_f32 v0, -|v2|, v0, v1
	v_mul_f32_e32 v2, v3, v3
	v_mul_f32_e32 v2, 0xbf38aa3b, v2
	v_fmamk_f32 v1, v4, 0x3f07dc22, v211
	v_fmaak_f32 v1, v4, v1, 0x3f35f0e3
	v_exp_f32_e32 v2, v2
	v_fmaak_f32 v1, v4, v1, 0xbe11a98e
	v_fmaak_f32 v1, v4, v1, 0x3e027906
	v_mul_f32_e32 v1, v4, v1
	v_mul_f32_e32 v1, v2, v1
	v_max_f32_e32 v2, 0, v3
	v_fma_f32 v1, -|v3|, v1, v2
	v_cvt_pk_bf16_f32 v131, v0, v1
	s_nop 1
	s_branch .LBB0_322
